# P9 hyena FFT: removed 8 redundant MFMA settle s_nop pairs (hazard distance >=48 without them), reduced one to s_nop 3
# baseline (speedup 1.0000x reference)
.LBB0_1793:
	s_add_i32 s0, s6, s44
	s_ashr_i32 s1, s0, 31
	v_and_b32_e32 v0, 0x1fdf, v209
	s_xor_b64 s[56:57], s[54:55], -1
	v_bfe_u32 v36, v209, 5, 1
	s_lshl_b64 s[4:5], s[0:1], 14
	v_sub_u32_e32 v1, 0, v0
	v_mov_b32_e32 v3, 0xfffffe00
	v_mov_b32_e32 v5, 0xfffffc00
	v_mov_b32_e32 v7, 0xfffffa00
	v_sub_u32_e32 v0, 0x1fe0, v0
	s_add_u32 s4, s26, s4
	v_xor_b32_e32 v1, 0x1000, v1
	v_mad_u32_u24 v3, v36, s81, v3
	v_mad_u32_u24 v5, v36, s81, v5
	v_mad_u32_u24 v7, v36, s81, v7
	v_mad_u32_u24 v9, v36, s81, v205
	v_mad_u32_u24 v11, v36, s81, v206
	v_mad_u32_u24 v13, v36, s81, v207
	v_mad_u32_u24 v15, v36, s81, v208
	v_xor_b32_e32 v0, 0x1000, v0
	s_addc_u32 s5, s27, s5
	v_mad_u32_u24 v2, v36, s81, v1
	v_add_u32_e32 v4, v3, v1
	v_add_u32_e32 v6, v5, v1
	v_add_u32_e32 v8, v7, v1
	v_add_u32_e32 v10, v9, v1
	v_add_u32_e32 v12, v11, v1
	v_add_u32_e32 v14, v13, v1
	v_add_u32_e32 v1, v15, v1
	s_waitcnt vmcnt(1)
	v_mad_u32_u24 v16, v36, s81, v0
	v_add_u32_e32 v3, v3, v0
	v_add_u32_e32 v5, v5, v0
	v_add_u32_e32 v7, v7, v0
	v_add_u32_e32 v9, v9, v0
	v_add_u32_e32 v11, v11, v0
	v_add_u32_e32 v13, v13, v0
	s_lshl_b64 s[0:1], s[0:1], 2
	v_add_u32_e32 v0, v15, v0
	v_and_b32_e32 v2, 0x1fff, v2
	v_and_b32_e32 v4, 0x1fff, v4
	v_and_b32_e32 v6, 0x1fff, v6
	v_and_b32_e32 v8, 0x1fff, v8
	v_and_b32_e32 v10, 0x1fff, v10
	v_and_b32_e32 v12, 0x1fff, v12
	v_and_b32_e32 v14, 0x1fff, v14
	v_and_b32_e32 v1, 0x1fff, v1
	v_and_b32_e32 v16, 0x1fff, v16
	v_and_b32_e32 v3, 0x1fff, v3
	v_and_b32_e32 v5, 0x1fff, v5
	v_and_b32_e32 v7, 0x1fff, v7
	v_and_b32_e32 v9, 0x1fff, v9
	v_and_b32_e32 v11, 0x1fff, v11
	v_and_b32_e32 v13, 0x1fff, v13
	s_add_u32 s6, s3, s0
	v_and_b32_e32 v0, 0x1fff, v0
	v_lshlrev_b32_e32 v2, 1, v2
	v_lshlrev_b32_e32 v4, 1, v4
	v_lshlrev_b32_e32 v6, 1, v6
	v_lshlrev_b32_e32 v8, 1, v8
	v_lshlrev_b32_e32 v10, 1, v10
	v_lshlrev_b32_e32 v12, 1, v12
	v_lshlrev_b32_e32 v14, 1, v14
	v_lshlrev_b32_e32 v1, 1, v1
	v_lshlrev_b32_e32 v16, 1, v16
	v_lshlrev_b32_e32 v3, 1, v3
	v_lshlrev_b32_e32 v5, 1, v5
	v_lshlrev_b32_e32 v7, 1, v7
	v_lshlrev_b32_e32 v9, 1, v9
	v_lshlrev_b32_e32 v11, 1, v11
	v_lshlrev_b32_e32 v13, 1, v13
	v_lshlrev_b32_e32 v0, 1, v0
	s_addc_u32 s7, s62, s1
	global_load_ushort v2, v2, s[4:5]
	s_nop 0
	global_load_ushort v4, v4, s[4:5]
	s_nop 0
	global_load_ushort v6, v6, s[4:5]
	s_nop 0
	global_load_ushort v8, v8, s[4:5]
	s_nop 0
	global_load_ushort v10, v10, s[4:5]
	s_nop 0
	global_load_ushort v12, v12, s[4:5]
	s_nop 0
	global_load_ushort v14, v14, s[4:5]
	s_nop 0
	global_load_ushort v1, v1, s[4:5]
	s_nop 0
	global_load_ushort v16, v16, s[4:5]
	s_nop 0
	global_load_ushort v3, v3, s[4:5]
	s_nop 0
	global_load_ushort v5, v5, s[4:5]
	s_nop 0
	global_load_ushort v7, v7, s[4:5]
	s_nop 0
	global_load_ushort v9, v9, s[4:5]
	s_nop 0
	global_load_ushort v11, v11, s[4:5]
	s_nop 0
	global_load_ushort v13, v13, s[4:5]
	v_lshlrev_b32_e32 v32, 3, v209
	global_load_ushort v15, v0, s[4:5]
	global_load_dword v17, v172, s[6:7]
	v_ashrrev_i32_e32 v33, 31, v32
	v_lshlrev_b64 v[34:35], 2, v[32:33]
	v_lshl_add_u64 v[148:149], s[16:17], 0, v[34:35]
	v_add_co_u32_e32 v0, vcc, s72, v148
	v_mov_b32_e32 v43, v209
	s_add_u32 s0, s70, s0
	s_addc_u32 s1, s71, s1
	s_and_b64 s[4:5], s[54:55], exec
	s_cselect_b32 s91, s88, 0x800
	s_add_i32 s90, s91, s44
	s_mov_b64 s[58:59], -1
	v_lshl_add_u64 v[164:165], s[18:19], 0, v[34:35]
	v_lshl_add_u64 v[166:167], s[20:21], 0, v[34:35]
	s_mov_b32 s60, 0
	s_waitcnt vmcnt(9)
	v_lshlrev_b32_e32 v19, 16, v1
	v_addc_co_u32_e32 v1, vcc, 0, v149, vcc
	s_waitcnt vmcnt(7)
	v_lshlrev_b32_e32 v21, 16, v3
	s_waitcnt vmcnt(6)
	v_lshlrev_b32_e32 v22, 16, v5
	global_load_dwordx4 v[104:107], v[0:1], off
	global_load_dwordx4 v[108:111], v[148:149], off
	global_load_dwordx4 v[100:103], v[148:149], off offset:16
	global_load_dwordx4 v[96:99], v[0:1], off offset:16
	s_waitcnt vmcnt(9)
	v_lshlrev_b32_e32 v23, 16, v7
	v_lshlrev_b32_e32 v10, 16, v10
	v_lshlrev_b32_e32 v2, 16, v2
	s_waitcnt vmcnt(4)
	v_div_scale_f32 v3, s[4:5], v17, v17, s82
	v_rcp_f32_e32 v5, v3
	v_lshlrev_b32_e32 v4, 16, v4
	v_lshlrev_b32_e32 v6, 16, v6
	v_lshlrev_b32_e32 v8, 16, v8
	v_fma_f32 v0, -v3, v5, 1.0
	v_fmac_f32_e32 v5, v0, v5
	v_div_scale_f32 v0, vcc, s82, v17, s82
	v_mul_f32_e32 v1, v0, v5
	v_fma_f32 v7, -v3, v1, v0
	v_fmac_f32_e32 v1, v7, v5
	v_fma_f32 v0, -v3, v1, v0
	v_div_fmas_f32 v0, v0, v5, v1
	v_div_fixup_f32 v42, v0, v17, s82
	v_mul_f32_e32 v1, v42, v10
	v_lshlrev_b32_e32 v20, 16, v16
	v_mul_f32_e32 v0, v42, v2
	v_cvt_pk_f16_f32 v16, v1, 0
	v_mul_f32_e32 v1, v42, v4
	v_mul_f32_e32 v2, v42, v6
	v_mul_f32_e32 v3, v42, v8
	v_lshlrev_b32_e32 v12, 16, v12
	v_cvt_pk_f16_f32 v0, v0, 0
	v_cvt_pk_f16_f32 v1, v1, 0
	v_cvt_pk_f16_f32 v2, v2, 0
	v_cvt_pk_f16_f32 v3, v3, 0
	v_lshlrev_b32_e32 v18, 16, v14
	v_lshlrev_b32_e32 v24, 16, v9
	v_lshlrev_b32_e32 v37, 16, v11
	v_lshlrev_b32_e32 v40, 16, v13
	v_lshlrev_b32_e32 v41, 16, v15
	v_mul_f32_e32 v17, v42, v12
	v_mfma_f32_32x32x16_f16 v[0:15], v[68:71], v[0:3], 0
	v_mul_f32_e32 v18, v42, v18
	v_mul_f32_e32 v19, v42, v19
	v_cvt_pk_f16_f32 v17, v17, 0
	v_cvt_pk_f16_f32 v18, v18, 0
	v_cvt_pk_f16_f32 v19, v19, 0
	v_mul_f32_e32 v20, v42, v20
	v_cvt_pk_f16_f32 v20, v20, 0
	v_mfma_f32_32x32x16_f16 v[0:15], v[84:87], v[16:19], v[0:15]
	v_mul_f32_e32 v16, v42, v21
	v_cvt_pk_f16_f32 v21, v16, 0
	v_mul_f32_e32 v16, v42, v22
	v_cvt_pk_f16_f32 v22, v16, 0
	v_mul_f32_e32 v16, v42, v23
	v_cvt_pk_f16_f32 v23, v16, 0
	v_mul_f32_e32 v38, v42, v24
	v_mul_f32_e32 v37, v42, v37
	v_mfma_f32_32x32x16_f16 v[16:31], v[72:75], v[20:23], 0
	v_cvt_pk_f16_f32 v39, v37, 0
	v_mul_f32_e32 v37, v42, v40
	v_cvt_pk_f16_f32 v40, v37, 0
	v_mul_f32_e32 v37, v42, v41
	v_cvt_pk_f16_f32 v38, v38, 0
	v_cvt_pk_f16_f32 v41, v37, 0
	v_and_b32_e32 v37, 0xffffffdf, v209
	v_cvt_pk_f16_f32 v0, v0, v1
	v_mfma_f32_32x32x16_f16 v[16:31], v[88:91], v[38:41], v[16:31]
	v_lshrrev_b32_e32 v38, 2, v209
	v_and_b32_e32 v38, 8, v38
	v_add_u32_e32 v38, 0, v38
	v_mad_u64_u32 v[40:41], s[4:5], v37, s83, v[38:39]
	v_cvt_pk_f16_f32 v1, v2, v3
	ds_write2_b32 v40, v0, v1 offset1:1
	v_cvt_pk_f16_f32 v0, v4, v5
	v_cvt_pk_f16_f32 v1, v6, v7
	ds_write2_b32 v40, v0, v1 offset0:4 offset1:5
	v_cvt_pk_f16_f32 v0, v8, v9
	v_cvt_pk_f16_f32 v1, v10, v11
	ds_write2_b32 v40, v0, v1 offset0:8 offset1:9
	v_cvt_pk_f16_f32 v0, v12, v13
	v_cvt_pk_f16_f32 v1, v14, v15
	v_or_b32_e32 v42, 32, v209
	ds_write2_b32 v40, v0, v1 offset0:12 offset1:13
	v_mad_u64_u32 v[0:1], s[4:5], v42, s83, v[38:39]
	v_cvt_pk_f16_f32 v1, v16, v17
	v_cvt_pk_f16_f32 v2, v18, v19
	ds_write2_b32 v0, v1, v2 offset1:1
	v_cvt_pk_f16_f32 v1, v20, v21
	v_cvt_pk_f16_f32 v2, v22, v23
	ds_write2_b32 v0, v1, v2 offset0:4 offset1:5
	v_cvt_pk_f16_f32 v1, v24, v25
	v_cvt_pk_f16_f32 v2, v26, v27
	ds_write2_b32 v0, v1, v2 offset0:8 offset1:9
	v_cvt_pk_f16_f32 v1, v28, v29
	v_cvt_pk_f16_f32 v2, v30, v31
	ds_write2_b32 v0, v1, v2 offset0:12 offset1:13
	s_waitcnt lgkmcnt(0)
	s_barrier
	s_lshl_b32 s4, s91, 2
	v_and_b32_e32 v0, 0xffffffdf, v43
	v_bfe_u32 v44, v43, 5, 1
	v_ashrrev_i32_e32 v46, 4, v0
	v_mad_u32_u24 v45, v44, s84, 0
	v_add_u32_e32 v0, v46, v0
	v_lshl_add_u32 v5, v0, 2, v45
	ds_read_b32 v0, v5
	ds_read_b32 v1, v5 offset:2176
	ds_read_b32 v2, v5 offset:4352
	ds_read_b32 v3, v5 offset:6528
	ds_read_b32 v6, v5 offset:21760
	ds_read_b32 v7, v5 offset:23936
	ds_read_b32 v4, v5 offset:17408
	s_waitcnt lgkmcnt(3)
	v_mfma_f32_32x32x16_f16 v[16:31], v[64:67], v[0:3], 0
	v_or_b32_e32 v0, 32, v43
	ds_read_b32 v5, v5 offset:19584
	v_ashrrev_i32_e32 v47, 4, v0
	v_add_u32_e32 v0, v47, v0
	v_lshl_add_u32 v39, v0, 2, v45
	ds_read_b32 v0, v39
	ds_read_b32 v1, v39 offset:2176
	ds_read_b32 v2, v39 offset:4352
	ds_read_b32 v3, v39 offset:6528
	ds_read_b32 v40, v39 offset:21760
	ds_read_b32 v41, v39 offset:23936
	ds_read_b32 v38, v39 offset:17408
	ds_read_b32 v39, v39 offset:19584
	s_waitcnt lgkmcnt(8)
	v_mfma_f32_32x32x16_f16 v[16:31], v[80:83], v[4:7], v[16:31]
	s_nop 15
	s_nop 3
	s_waitcnt lgkmcnt(4)
	v_mfma_f32_32x32x16_f16 v[0:15], v[64:67], v[0:3], 0
	s_waitcnt lgkmcnt(0)
	v_mfma_f32_32x32x16_f16 v[0:15], v[80:83], v[38:41], v[0:15]
	v_and_b32_e32 v38, 15, v43
	v_mul_lo_u32 v40, v46, s86
	v_mad_i32_i24 v39, v44, s85, v45
	v_or_b32_e32 v40, v40, v38
	v_mul_f32_e32 v41, v16, v173
	v_mul_f32_e32 v45, v16, v174
	v_fma_f32 v41, -v17, v174, v41
	v_fma_f32 v45, v17, v173, v45
	v_lshl_add_u32 v40, v40, 2, v39
	s_nop 2
	v_cvt_pk_f16_f32 v16, v41, v45
	v_mul_f32_e32 v17, v18, v175
	v_mul_f32_e32 v41, v18, v176
	v_fma_f32 v17, -v19, v176, v17
	v_fma_f32 v41, v19, v175, v41
	v_add_u32_e32 v18, 0x8800, v40
	v_cvt_pk_f16_f32 v17, v17, v41
	ds_write2_b32 v18, v16, v17 offset1:17
	v_mul_f32_e32 v16, v20, v177
	v_mul_f32_e32 v17, v20, v178
	v_fma_f32 v16, -v21, v178, v16
	v_fma_f32 v17, v21, v177, v17
	v_ashrrev_i32_e32 v45, 8, v43
	v_cvt_pk_f16_f32 v16, v16, v17
	v_mul_f32_e32 v17, v22, v179
	v_mul_f32_e32 v19, v22, v180
	v_fma_f32 v17, -v23, v180, v17
	v_fma_f32 v19, v23, v179, v19
	v_and_b32_e32 v20, 0xdf, v43
	v_cvt_pk_f16_f32 v17, v17, v19
	ds_write2_b32 v18, v16, v17 offset0:68 offset1:85
	v_mul_f32_e32 v16, v24, v181
	v_mul_f32_e32 v17, v24, v182
	v_fma_f32 v16, -v25, v182, v16
	v_fma_f32 v17, v25, v181, v17
	v_mad_i32_i24 v43, v45, s87, 0
	v_cvt_pk_f16_f32 v16, v16, v17
	v_mul_f32_e32 v17, v26, v183
	v_mul_f32_e32 v19, v26, v184
	v_fma_f32 v17, -v27, v184, v17
	v_fma_f32 v19, v27, v183, v19
	v_mad_u32_u24 v21, v44, s84, v43
	v_cvt_pk_f16_f32 v17, v17, v19
	ds_write2_b32 v18, v16, v17 offset0:136 offset1:153
	v_mul_f32_e32 v16, v28, v185
	v_mul_f32_e32 v17, v28, v186
	v_fma_f32 v16, -v29, v186, v16
	v_fma_f32 v17, v29, v185, v17
	s_nop 0
	v_cvt_pk_f16_f32 v16, v16, v17
	v_mul_f32_e32 v17, v30, v187
	v_mul_f32_e32 v19, v30, v188
	v_fma_f32 v17, -v31, v188, v17
	v_fma_f32 v19, v31, v187, v19
	s_nop 0
	v_cvt_pk_f16_f32 v17, v17, v19
	ds_write2_b32 v18, v16, v17 offset0:204 offset1:221
	v_mul_lo_u32 v16, v47, s86
	v_or_b32_e32 v16, v16, v38
	v_lshl_add_u32 v16, v16, 2, v39
	v_mul_f32_e32 v17, v0, v189
	v_mul_f32_e32 v18, v0, v190
	v_fma_f32 v17, -v1, v190, v17
	v_fma_f32 v18, v1, v189, v18
	s_nop 0
	v_cvt_pk_f16_f32 v0, v17, v18
	v_mul_f32_e32 v1, v2, v191
	v_mul_f32_e32 v17, v2, v192
	v_fma_f32 v1, -v3, v192, v1
	v_fma_f32 v17, v3, v191, v17
	v_add_u32_e32 v2, 0x8800, v16
	v_cvt_pk_f16_f32 v1, v1, v17
	ds_write2_b32 v2, v0, v1 offset1:17
	v_mul_f32_e32 v0, v4, v193
	v_mul_f32_e32 v1, v4, v194
	v_fma_f32 v0, -v5, v194, v0
	v_fma_f32 v1, v5, v193, v1
	s_nop 0
	v_cvt_pk_f16_f32 v0, v0, v1
	v_mul_f32_e32 v1, v6, v195
	v_mul_f32_e32 v3, v6, v196
	v_fma_f32 v1, -v7, v196, v1
	v_fma_f32 v3, v7, v195, v3
	s_nop 0
	v_cvt_pk_f16_f32 v1, v1, v3
	ds_write2_b32 v2, v0, v1 offset0:68 offset1:85
	v_mul_f32_e32 v0, v8, v197
	v_mul_f32_e32 v1, v8, v198
	v_fma_f32 v0, -v9, v198, v0
	v_fma_f32 v1, v9, v197, v1
	s_nop 0
	v_cvt_pk_f16_f32 v0, v0, v1
	v_mul_f32_e32 v1, v10, v199
	v_mul_f32_e32 v3, v10, v200
	v_fma_f32 v1, -v11, v200, v1
	v_fma_f32 v3, v11, v199, v3
	s_nop 0
	v_cvt_pk_f16_f32 v1, v1, v3
	ds_write2_b32 v2, v0, v1 offset0:136 offset1:153
	v_mul_f32_e32 v0, v12, v201
	v_mul_f32_e32 v1, v12, v202
	v_fma_f32 v0, -v13, v202, v0
	v_fma_f32 v1, v13, v201, v1
	s_nop 0
	v_cvt_pk_f16_f32 v0, v0, v1
	v_mul_f32_e32 v1, v14, v203
	v_mul_f32_e32 v3, v14, v204
	v_fma_f32 v1, -v15, v204, v1
	v_fma_f32 v3, v15, v203, v3
	s_nop 0
	v_cvt_pk_f16_f32 v1, v1, v3
	ds_write2_b32 v2, v0, v1 offset0:204 offset1:221
	v_lshrrev_b32_e32 v0, 4, v20
	v_add_lshl_u32 v46, v0, v20, 2
	v_add_u32_e32 v17, v21, v46
	s_waitcnt lgkmcnt(0)
	s_barrier
	ds_read_b32 v0, v17 offset:34816
	ds_read_b32 v1, v17 offset:36992
	ds_read_b32 v2, v17 offset:39168
	ds_read_b32 v3, v17 offset:41344
	ds_read_b32 v18, v17 offset:56576
	ds_read_b32 v19, v17 offset:58752
	ds_read_b32 v16, v17 offset:52224
	s_waitcnt lgkmcnt(3)
	v_mfma_f32_32x32x16_f16 v[0:15], v[76:79], v[0:3], 0
	ds_read_b32 v17, v17 offset:54400
	v_or_b32_e32 v20, 32, v20
	v_lshrrev_b32_e32 v22, 4, v20
	v_add_lshl_u32 v47, v22, v20, 2
	v_add_u32_e32 v39, v21, v47
	s_waitcnt lgkmcnt(0)
	v_mfma_f32_32x32x16_f16 v[0:15], v[92:95], v[16:19], v[0:15]
	ds_read_b32 v16, v39 offset:34816
	ds_read_b32 v17, v39 offset:36992
	ds_read_b32 v18, v39 offset:39168
	ds_read_b32 v19, v39 offset:41344
	ds_read_b32 v40, v39 offset:56576
	ds_read_b32 v41, v39 offset:58752
	ds_read_b32 v38, v39 offset:52224
	ds_read_b32 v39, v39 offset:54400
	s_nop 3
	v_cvt_pk_f16_f32 v0, v0, v1
	s_waitcnt lgkmcnt(4)
	v_mfma_f32_32x32x16_f16 v[16:31], v[76:79], v[16:19], 0
	s_waitcnt lgkmcnt(0)
	v_mfma_f32_32x32x16_f16 v[16:31], v[92:95], v[38:41], v[16:31]
	v_mul_i32_i24_e32 v38, 0x3fc0, v45
	v_mul_u32_u24_e32 v39, 0x880, v44
	v_add3_u32 v38, v43, v38, v39
	v_add_u32_e32 v39, v38, v46
	ds_write_b32 v39, v0
	v_cvt_pk_f16_f32 v0, v2, v3
	ds_write_b32 v39, v0 offset:1088
	v_cvt_pk_f16_f32 v0, v4, v5
	ds_write_b32 v39, v0 offset:4352
	v_cvt_pk_f16_f32 v0, v6, v7
	ds_write_b32 v39, v0 offset:5440
	v_cvt_pk_f16_f32 v0, v8, v9
	ds_write_b32 v39, v0 offset:8704
	v_cvt_pk_f16_f32 v0, v10, v11
	ds_write_b32 v39, v0 offset:9792
	v_cvt_pk_f16_f32 v0, v12, v13
	ds_write_b32 v39, v0 offset:13056
	v_cvt_pk_f16_f32 v0, v14, v15
	ds_write_b32 v39, v0 offset:14144
	v_add_u32_e32 v0, v38, v47
	v_cvt_pk_f16_f32 v1, v16, v17
	ds_write_b32 v0, v1
	v_cvt_pk_f16_f32 v1, v18, v19
	ds_write_b32 v0, v1 offset:1088
	v_cvt_pk_f16_f32 v1, v20, v21
	ds_write_b32 v0, v1 offset:4352
	v_cvt_pk_f16_f32 v1, v22, v23
	ds_write_b32 v0, v1 offset:5440
	v_cvt_pk_f16_f32 v1, v24, v25
	ds_write_b32 v0, v1 offset:8704
	v_cvt_pk_f16_f32 v1, v26, v27
	ds_write_b32 v0, v1 offset:9792
	v_cvt_pk_f16_f32 v1, v28, v29
	ds_write_b32 v0, v1 offset:13056
	v_cvt_pk_f16_f32 v1, v30, v31
	ds_write_b32 v0, v1 offset:14144
	v_ashrrev_i32_e32 v1, 4, v37
	v_mul_u32_u24_e32 v0, 0x2200, v36
	v_add_lshl_u32 v1, v1, v37, 2
	v_add3_u32 v1, 0, v1, v0
	s_waitcnt lgkmcnt(0)
	s_barrier
	ds_read_b32 v2, v1
	ds_read_b32 v3, v1 offset:17408
	ds_read_b32 v4, v1 offset:2176
	ds_read_b32 v5, v1 offset:19584
	ds_read_b32 v6, v1 offset:4352
	ds_read_b32 v7, v1 offset:21760
	ds_read_b32 v8, v1 offset:23936
	ds_read_b32 v1, v1 offset:6528
	s_waitcnt lgkmcnt(7)
	v_cvt_f32_f16_e32 v9, v2
	s_waitcnt lgkmcnt(6)
	v_cvt_f32_f16_e32 v10, v3
	v_cvt_f32_f16_sdwa v2, v2 dst_sel:DWORD dst_unused:UNUSED_PAD src0_sel:WORD_1
	v_cvt_f32_f16_sdwa v3, v3 dst_sel:DWORD dst_unused:UNUSED_PAD src0_sel:WORD_1
	v_mov_b32_e32 v14, s4
	v_add_f32_e32 v11, v9, v10
	v_sub_f32_e32 v9, v9, v10
	v_mul_f32_e32 v210, 0x3c000000, v11
	v_add_f32_e32 v11, v2, v3
	v_mul_f32_e32 v212, 0x3c000000, v9
	v_sub_f32_e32 v2, v2, v3
	s_waitcnt lgkmcnt(5)
	v_cvt_f32_f16_e32 v3, v4
	s_waitcnt lgkmcnt(4)
	v_cvt_f32_f16_e32 v9, v5
	v_cvt_f32_f16_sdwa v4, v4 dst_sel:DWORD dst_unused:UNUSED_PAD src0_sel:WORD_1
	v_cvt_f32_f16_sdwa v5, v5 dst_sel:DWORD dst_unused:UNUSED_PAD src0_sel:WORD_1
	s_add_i32 s4, s91, s45
	v_mul_f32_e32 v213, 0x3c000000, v2
	v_add_f32_e32 v2, v3, v9
	s_ashr_i32 s5, s4, 31
	v_mul_f32_e32 v214, 0x3c000000, v2
	v_add_f32_e32 v2, v4, v5
	s_lshl_b64 s[4:5], s[4:5], 2
	v_mul_f32_e32 v215, 0x3c000000, v2
	v_sub_f32_e32 v2, v3, v9
	s_add_u32 s4, s36, s4
	v_mul_f32_e32 v216, 0x3c000000, v2
	v_sub_f32_e32 v2, v4, v5
	s_addc_u32 s5, s37, s5
	s_add_i32 s6, s90, 0x1800
	v_mul_f32_e32 v217, 0x3c000000, v2
	s_waitcnt lgkmcnt(3)
	v_cvt_f32_f16_e32 v2, v6
	v_cvt_f32_f16_sdwa v3, v6 dst_sel:DWORD dst_unused:UNUSED_PAD src0_sel:WORD_1
	v_ashrrev_i32_e32 v6, 4, v42
	s_ashr_i32 s7, s6, 31
	v_add_lshl_u32 v6, v6, v42, 2
	s_lshl_b64 s[6:7], s[6:7], 2
	v_add3_u32 v0, 0, v6, v0
	s_add_u32 s6, s36, s6
	v_mul_f32_e32 v211, 0x3c000000, v11
	s_waitcnt lgkmcnt(2)
	v_cvt_f32_f16_e32 v4, v7
	v_cvt_f32_f16_sdwa v5, v7 dst_sel:DWORD dst_unused:UNUSED_PAD src0_sel:WORD_1
	ds_read_b32 v6, v0
	ds_read_b32 v7, v0 offset:17408
	ds_read_b32 v9, v0 offset:2176
	ds_read_b32 v10, v0 offset:19584
	ds_read_b32 v11, v0 offset:4352
	ds_read_b32 v12, v0 offset:21760
	ds_read_b32 v13, v0 offset:23936
	ds_read_b32 v0, v0 offset:6528
	s_waitcnt lgkmcnt(0)
	s_barrier
	s_addc_u32 s7, s37, s7
	global_load_dword v150, v14, s[46:47]
	global_load_dword v152, v14, s[48:49]
	global_load_dword v154, v172, s[0:1]
	global_load_dword v156, v172, s[4:5]
	global_load_dword v158, v172, s[6:7]
	v_add_f32_e32 v14, v2, v4
	v_sub_f32_e32 v2, v2, v4
	v_mul_f32_e32 v218, 0x3c000000, v14
	v_add_f32_e32 v14, v3, v5
	v_mul_f32_e32 v220, 0x3c000000, v2
	v_sub_f32_e32 v2, v3, v5
	v_cvt_f32_f16_e32 v3, v1
	v_cvt_f32_f16_e32 v4, v8
	v_cvt_f32_f16_sdwa v1, v1 dst_sel:DWORD dst_unused:UNUSED_PAD src0_sel:WORD_1
	v_cvt_f32_f16_sdwa v5, v8 dst_sel:DWORD dst_unused:UNUSED_PAD src0_sel:WORD_1
	v_mul_f32_e32 v221, 0x3c000000, v2
	v_add_f32_e32 v2, v3, v4
	v_mul_f32_e32 v222, 0x3c000000, v2
	v_add_f32_e32 v2, v1, v5
	v_mul_f32_e32 v223, 0x3c000000, v2
	v_sub_f32_e32 v2, v3, v4
	v_mul_f32_e32 v224, 0x3c000000, v2
	v_cvt_f32_f16_e32 v2, v6
	v_cvt_f32_f16_e32 v3, v7
	v_sub_f32_e32 v1, v1, v5
	v_cvt_f32_f16_sdwa v4, v6 dst_sel:DWORD dst_unused:UNUSED_PAD src0_sel:WORD_1
	v_cvt_f32_f16_sdwa v5, v7 dst_sel:DWORD dst_unused:UNUSED_PAD src0_sel:WORD_1
	v_mul_f32_e32 v225, 0x3c000000, v1
	v_add_f32_e32 v1, v2, v3
	v_mul_f32_e32 v226, 0x3c000000, v1
	v_add_f32_e32 v1, v4, v5
	v_mul_f32_e32 v227, 0x3c000000, v1
	v_sub_f32_e32 v1, v2, v3
	v_cvt_f32_f16_e32 v2, v9
	v_cvt_f32_f16_e32 v3, v10
	v_mul_f32_e32 v228, 0x3c000000, v1
	v_sub_f32_e32 v1, v4, v5
	v_cvt_f32_f16_sdwa v4, v9 dst_sel:DWORD dst_unused:UNUSED_PAD src0_sel:WORD_1
	v_cvt_f32_f16_sdwa v5, v10 dst_sel:DWORD dst_unused:UNUSED_PAD src0_sel:WORD_1
	v_mul_f32_e32 v229, 0x3c000000, v1
	v_add_f32_e32 v1, v2, v3
	v_mul_f32_e32 v230, 0x3c000000, v1
	v_add_f32_e32 v1, v4, v5
	v_mul_f32_e32 v231, 0x3c000000, v1
	v_sub_f32_e32 v1, v2, v3
	v_cvt_f32_f16_e32 v2, v11
	v_cvt_f32_f16_e32 v3, v12
	v_mul_f32_e32 v232, 0x3c000000, v1
	v_sub_f32_e32 v1, v4, v5
	v_cvt_f32_f16_sdwa v4, v11 dst_sel:DWORD dst_unused:UNUSED_PAD src0_sel:WORD_1
	v_cvt_f32_f16_sdwa v5, v12 dst_sel:DWORD dst_unused:UNUSED_PAD src0_sel:WORD_1
	v_mul_f32_e32 v233, 0x3c000000, v1
	v_add_f32_e32 v1, v2, v3
	v_mul_f32_e32 v234, 0x3c000000, v1
	v_add_f32_e32 v1, v4, v5
	v_mul_f32_e32 v235, 0x3c000000, v1
	v_sub_f32_e32 v1, v2, v3
	v_cvt_f32_f16_e32 v2, v0
	v_cvt_f32_f16_e32 v3, v13
	v_mul_f32_e32 v236, 0x3c000000, v1
	v_sub_f32_e32 v1, v4, v5
	v_cvt_f32_f16_sdwa v0, v0 dst_sel:DWORD dst_unused:UNUSED_PAD src0_sel:WORD_1
	v_cvt_f32_f16_sdwa v4, v13 dst_sel:DWORD dst_unused:UNUSED_PAD src0_sel:WORD_1
	v_mul_f32_e32 v237, 0x3c000000, v1
	v_add_f32_e32 v1, v2, v3
	v_mul_f32_e32 v238, 0x3c000000, v1
	v_add_f32_e32 v1, v0, v4
	v_mul_f32_e32 v239, 0x3c000000, v1
	v_sub_f32_e32 v1, v2, v3
	v_sub_f32_e32 v0, v0, v4
	v_mul_f32_e32 v240, 0x3c000000, v1
	v_mul_f32_e32 v241, 0x3c000000, v0
	v_lshlrev_b64 v[0:1], 1, v[32:33]
	v_mul_f32_e32 v219, 0x3c000000, v14
	v_cmp_lt_i32_e64 s[0:1], 0, v209
	v_cmp_gt_i32_e64 s[4:5], s63, v209
	v_lshl_add_u64 v[160:161], s[12:13], 0, v[0:1]
	v_lshl_add_u64 v[162:163], s[14:15], 0, v[0:1]
	s_add_i32 s91, s91, s50
	s_waitcnt vmcnt(4)
	v_mov_b32_e32 v151, v150
	s_waitcnt vmcnt(3)
	v_mov_b32_e32 v153, v152
	s_waitcnt vmcnt(2)
	v_mov_b32_e32 v155, v154
	s_waitcnt vmcnt(1)
	v_mov_b32_e32 v157, v156
	s_waitcnt vmcnt(0)
	v_mov_b32_e32 v159, v158
	v_mov_b32_e32 v168, v156
	v_mov_b32_e32 v169, v150
	v_mov_b32_e32 v170, v150
	v_mov_b32_e32 v171, v156

.LBB0_1796:
	v_lshl_add_u32 v242, v209, 5, 0
	v_add_u32_e32 v0, 0x19800, v242
	ds_write_b128 v242, v[108:111] offset:34816
	ds_write_b128 v242, v[100:103] offset:34832
	ds_write_b128 v0, v[104:107]
	v_add_u32_e32 v0, 0x19810, v242
	v_bfe_u32 v129, v209, 5, 1
	v_lshlrev_b32_e32 v5, 2, v209
	ds_write_b128 v0, v[96:99]
	v_lshlrev_b32_e32 v4, 13, v129
	v_and_b32_e32 v0, 0xffffff7c, v5
	v_add_u32_e32 v6, v4, v0
	v_add_u32_e32 v2, 0, v6
	s_waitcnt lgkmcnt(0)
	s_barrier
	ds_read2st64_b32 v[0:1], v2 offset0:136 offset1:144
	ds_read2st64_b32 v[2:3], v2 offset0:152 offset1:160
	v_or_b32_e32 v5, 0x80, v5
	v_add_u32_e32 v4, v4, v5
	s_waitcnt lgkmcnt(0)
	v_mfma_f32_32x32x16_f16 v[48:63], v[68:71], v[0:3], 0
	v_add_u32_e32 v2, 0, v4
	ds_read2st64_b32 v[0:1], v2 offset0:136 offset1:144
	ds_read2st64_b32 v[2:3], v2 offset0:152 offset1:160
	s_add_i32 s6, 0, 0x19800
	v_lshrrev_b32_e32 v112, 2, v209
	v_and_b32_e32 v112, 8, v112
	v_or_b32_e32 v128, 32, v209
	v_add_u32_e32 v247, 0, v112
	s_waitcnt lgkmcnt(0)
	v_mfma_f32_32x32x16_f16 v[32:47], v[72:75], v[0:3], 0
	v_add_u32_e32 v2, s6, v6
	ds_read2st64_b32 v[0:1], v2 offset1:8
	ds_read2st64_b32 v[2:3], v2 offset0:16 offset1:24
	v_mul_lo_u32 v249, v128, s83
	v_add_u32_e32 v250, v247, v249
	v_and_b32_e32 v130, 0xffffffdf, v209
	v_mul_lo_u32 v248, v130, s83
	v_add_u32_e32 v251, v247, v248
	s_waitcnt lgkmcnt(0)
	v_mfma_f32_32x32x16_f16 v[16:31], v[68:71], v[0:3], 0
	v_add_u32_e32 v2, s6, v4
	ds_read2st64_b32 v[0:1], v2 offset1:8
	ds_read2st64_b32 v[2:3], v2 offset0:16 offset1:24
	v_cvt_pk_f16_f32 v32, v32, v33
	v_cvt_pk_f16_f32 v33, v34, v35
	ds_write2_b32 v250, v32, v33 offset1:1
	v_cvt_pk_f16_f32 v32, v36, v37
	v_cvt_pk_f16_f32 v33, v38, v39
	s_waitcnt lgkmcnt(1)
	v_mfma_f32_32x32x16_f16 v[0:15], v[72:75], v[0:3], 0
	ds_write2_b32 v250, v32, v33 offset0:4 offset1:5
	v_cvt_pk_f16_f32 v32, v40, v41
	v_cvt_pk_f16_f32 v33, v42, v43
	ds_write2_b32 v250, v32, v33 offset0:8 offset1:9
	v_cvt_pk_f16_f32 v32, v44, v45
	v_cvt_pk_f16_f32 v33, v46, v47
	ds_write2_b32 v250, v32, v33 offset0:12 offset1:13
	v_add_u32_e32 v32, 0x11000, v247
	v_add_u32_e32 v33, v32, v248
	v_cvt_pk_f16_f32 v16, v16, v17
	v_cvt_pk_f16_f32 v17, v18, v19
	ds_write2_b32 v33, v16, v17 offset1:1
	v_cvt_pk_f16_f32 v16, v20, v21
	v_cvt_pk_f16_f32 v17, v22, v23
	ds_write2_b32 v33, v16, v17 offset0:4 offset1:5
	v_cvt_pk_f16_f32 v16, v24, v25
	v_cvt_pk_f16_f32 v17, v26, v27
	ds_write2_b32 v33, v16, v17 offset0:8 offset1:9
	v_cvt_pk_f16_f32 v16, v28, v29
	v_cvt_pk_f16_f32 v17, v30, v31
	v_cvt_pk_f16_f32 v48, v48, v49
	v_cvt_pk_f16_f32 v49, v50, v51
	ds_write2_b32 v33, v16, v17 offset0:12 offset1:13
	v_add_u32_e32 v16, v32, v249
	v_cvt_pk_f16_f32 v0, v0, v1
	v_cvt_pk_f16_f32 v1, v2, v3
	ds_write2_b32 v251, v48, v49 offset1:1
	v_cvt_pk_f16_f32 v48, v52, v53
	v_cvt_pk_f16_f32 v49, v54, v55
	ds_write2_b32 v16, v0, v1 offset1:1
	v_cvt_pk_f16_f32 v0, v4, v5
	v_cvt_pk_f16_f32 v1, v6, v7
	ds_write2_b32 v251, v48, v49 offset0:4 offset1:5
	v_cvt_pk_f16_f32 v48, v56, v57
	v_cvt_pk_f16_f32 v49, v58, v59
	ds_write2_b32 v16, v0, v1 offset0:4 offset1:5
	v_cvt_pk_f16_f32 v0, v8, v9
	v_cvt_pk_f16_f32 v1, v10, v11
	ds_write2_b32 v251, v48, v49 offset0:8 offset1:9
	v_cvt_pk_f16_f32 v48, v60, v61
	v_cvt_pk_f16_f32 v49, v62, v63
	ds_write2_b32 v16, v0, v1 offset0:8 offset1:9
	v_cvt_pk_f16_f32 v0, v12, v13
	v_cvt_pk_f16_f32 v1, v14, v15
	v_mov_b32_e32 v116, v209
	ds_write2_b32 v251, v48, v49 offset0:12 offset1:13
	ds_write2_b32 v16, v0, v1 offset0:12 offset1:13
	s_waitcnt lgkmcnt(0)
	s_barrier
	s_lshl_b32 s8, s60, 14
	v_and_b32_e32 v0, 0xffffffdf, v116
	v_bfe_u32 v117, v116, 5, 1
	v_ashrrev_i32_e32 v119, 4, v0
	v_mad_u32_u24 v118, v117, s84, 0
	v_add_lshl_u32 v8, v119, v0, 2
	v_add_u32_e32 v5, v118, v8
	ds_read_b32 v0, v5
	ds_read_b32 v1, v5 offset:2176
	ds_read_b32 v2, v5 offset:4352
	ds_read_b32 v3, v5 offset:6528
	ds_read_b32 v6, v5 offset:21760
	ds_read_b32 v7, v5 offset:23936
	ds_read_b32 v4, v5 offset:17408
	s_waitcnt lgkmcnt(3)
	v_mfma_f32_32x32x16_f16 v[48:63], v[64:67], v[0:3], 0
	ds_read_b32 v5, v5 offset:19584
	v_or_b32_e32 v0, 32, v116
	v_ashrrev_i32_e32 v120, 4, v0
	v_add_lshl_u32 v9, v120, v0, 2
	v_add_u32_e32 v10, v118, v9
	s_add_i32 s6, s8, s90
	s_ashr_i32 s7, s6, 31
	s_waitcnt lgkmcnt(0)
	v_mfma_f32_32x32x16_f16 v[48:63], v[80:83], v[4:7], v[48:63]
	ds_read_b32 v0, v10
	ds_read_b32 v1, v10 offset:2176
	ds_read_b32 v2, v10 offset:4352
	ds_read_b32 v3, v10 offset:6528
	ds_read_b32 v6, v10 offset:21760
	ds_read_b32 v7, v10 offset:23936
	ds_read_b32 v4, v10 offset:17408
	ds_read_b32 v5, v10 offset:19584
	v_add_u32_e32 v10, 0x11000, v118
	v_add_u32_e32 v8, v10, v8
	v_add_u32_e32 v113, v10, v9
	s_lshl_b64 s[6:7], s[6:7], 13
	s_andn2_b64 vcc, exec, s[52:53]
	s_waitcnt lgkmcnt(4)
	v_mfma_f32_32x32x16_f16 v[32:47], v[64:67], v[0:3], 0
	v_mov_b32_e32 v122, 0
	v_mov_b32_e32 v123, 0
	s_waitcnt lgkmcnt(0)
	v_mfma_f32_32x32x16_f16 v[32:47], v[80:83], v[4:7], v[32:47]
	ds_read_b32 v0, v8
	ds_read_b32 v1, v8 offset:2176
	ds_read_b32 v2, v8 offset:4352
	ds_read_b32 v3, v8 offset:6528
	ds_read_b32 v6, v8 offset:21760
	ds_read_b32 v7, v8 offset:23936
	ds_read_b32 v4, v8 offset:17408
	ds_read_b32 v5, v8 offset:19584
	s_waitcnt lgkmcnt(4)
	v_mfma_f32_32x32x16_f16 v[16:31], v[64:67], v[0:3], 0
	ds_read_b32 v0, v113
	ds_read_b32 v1, v113 offset:2176
	ds_read_b32 v2, v113 offset:4352
	ds_read_b32 v3, v113 offset:6528
	ds_read_b32 v114, v113 offset:21760
	ds_read_b32 v115, v113 offset:23936
	ds_read_b32 v112, v113 offset:17408
	ds_read_b32 v113, v113 offset:19584
	s_waitcnt lgkmcnt(8)
	v_mfma_f32_32x32x16_f16 v[16:31], v[80:83], v[4:7], v[16:31]
	s_waitcnt lgkmcnt(4)
	v_mfma_f32_32x32x16_f16 v[0:15], v[64:67], v[0:3], 0
	s_waitcnt lgkmcnt(0)
	v_mfma_f32_32x32x16_f16 v[0:15], v[80:83], v[112:115], v[0:15]
	v_and_b32_e32 v112, 15, v116
	v_mul_lo_u32 v114, v119, s86
	v_or_b32_e32 v114, v114, v112
	v_mad_i32_i24 v113, v117, s85, v118
	v_lshlrev_b32_e32 v114, 2, v114
	v_mul_f32_e32 v119, v48, v173
	v_mul_f32_e32 v121, v48, v174
	v_fma_f32 v119, -v49, v174, v119
	v_fma_f32 v121, v49, v173, v121
	v_add_u32_e32 v115, v113, v114
	v_cvt_pk_f16_f32 v48, v119, v121
	v_mul_f32_e32 v49, v50, v175
	v_mul_f32_e32 v119, v50, v176
	v_fma_f32 v49, -v51, v176, v49
	v_fma_f32 v119, v51, v175, v119
	v_add_u32_e32 v50, 0x8800, v115
	v_cvt_pk_f16_f32 v49, v49, v119
	ds_write2_b32 v50, v48, v49 offset1:17
	v_mul_f32_e32 v48, v52, v177
	v_mul_f32_e32 v49, v52, v178
	v_fma_f32 v48, -v53, v178, v48
	v_fma_f32 v49, v53, v177, v49
	v_ashrrev_i32_e32 v119, 8, v116
	v_cvt_pk_f16_f32 v48, v48, v49
	v_mul_f32_e32 v49, v54, v179
	v_mul_f32_e32 v51, v54, v180
	v_fma_f32 v49, -v55, v180, v49
	v_fma_f32 v51, v55, v179, v51
	v_mov_b32_e32 v121, 0
	v_cvt_pk_f16_f32 v49, v49, v51
	ds_write2_b32 v50, v48, v49 offset0:68 offset1:85
	v_mul_f32_e32 v48, v56, v181
	v_mul_f32_e32 v49, v56, v182
	v_fma_f32 v48, -v57, v182, v48
	v_fma_f32 v49, v57, v181, v49
	s_nop 0
	v_cvt_pk_f16_f32 v48, v48, v49
	v_mul_f32_e32 v49, v58, v183
	v_mul_f32_e32 v51, v58, v184
	v_fma_f32 v49, -v59, v184, v49
	v_fma_f32 v51, v59, v183, v51
	s_nop 0
	v_cvt_pk_f16_f32 v49, v49, v51
	ds_write2_b32 v50, v48, v49 offset0:136 offset1:153
	v_mul_f32_e32 v48, v60, v185
	v_mul_f32_e32 v49, v60, v186
	v_fma_f32 v48, -v61, v186, v48
	v_fma_f32 v49, v61, v185, v49
	s_nop 0
	v_cvt_pk_f16_f32 v48, v48, v49
	v_mul_f32_e32 v49, v62, v187
	v_mul_f32_e32 v51, v62, v188
	v_fma_f32 v49, -v63, v188, v49
	v_fma_f32 v51, v63, v187, v51
	s_nop 0
	v_cvt_pk_f16_f32 v49, v49, v51
	ds_write2_b32 v50, v48, v49 offset0:204 offset1:221
	v_mul_lo_u32 v48, v120, s86
	v_or_b32_e32 v48, v48, v112
	v_lshlrev_b32_e32 v48, 2, v48
	v_add_u32_e32 v49, v113, v48
	v_mul_f32_e32 v50, v32, v189
	v_mul_f32_e32 v51, v32, v190
	v_fma_f32 v50, -v33, v190, v50
	v_fma_f32 v51, v33, v189, v51
	v_mov_b32_e32 v120, 0
	v_cvt_pk_f16_f32 v32, v50, v51
	v_mul_f32_e32 v33, v34, v191
	v_mul_f32_e32 v50, v34, v192
	v_fma_f32 v33, -v35, v192, v33
	v_fma_f32 v50, v35, v191, v50
	v_add_u32_e32 v34, 0x8800, v49
	v_cvt_pk_f16_f32 v33, v33, v50
	ds_write2_b32 v34, v32, v33 offset1:17
	v_mul_f32_e32 v32, v36, v193
	v_mul_f32_e32 v33, v36, v194
	v_fma_f32 v32, -v37, v194, v32
	v_fma_f32 v33, v37, v193, v33
	s_nop 0
	v_cvt_pk_f16_f32 v32, v32, v33
	v_mul_f32_e32 v33, v38, v195
	v_mul_f32_e32 v35, v38, v196
	v_fma_f32 v33, -v39, v196, v33
	v_fma_f32 v35, v39, v195, v35
	s_nop 0
	v_cvt_pk_f16_f32 v33, v33, v35
	ds_write2_b32 v34, v32, v33 offset0:68 offset1:85
	v_mul_f32_e32 v32, v40, v197
	v_mul_f32_e32 v33, v40, v198
	v_fma_f32 v32, -v41, v198, v32
	v_fma_f32 v33, v41, v197, v33
	s_nop 0
	v_cvt_pk_f16_f32 v32, v32, v33
	v_mul_f32_e32 v33, v42, v199
	v_mul_f32_e32 v35, v42, v200
	v_fma_f32 v33, -v43, v200, v33
	v_fma_f32 v35, v43, v199, v35
	s_nop 0
	v_cvt_pk_f16_f32 v33, v33, v35
	ds_write2_b32 v34, v32, v33 offset0:136 offset1:153
	v_mul_f32_e32 v32, v44, v201
	v_mul_f32_e32 v33, v44, v202
	v_fma_f32 v32, -v45, v202, v32
	v_fma_f32 v33, v45, v201, v33
	s_nop 0
	v_cvt_pk_f16_f32 v32, v32, v33
	v_mul_f32_e32 v33, v46, v203
	v_mul_f32_e32 v35, v46, v204
	v_fma_f32 v33, -v47, v204, v33
	v_fma_f32 v35, v47, v203, v35
	s_nop 0
	v_cvt_pk_f16_f32 v33, v33, v35
	ds_write2_b32 v34, v32, v33 offset0:204 offset1:221
	v_add_u32_e32 v32, 0x19800, v113
	v_mul_f32_e32 v34, v16, v173
	v_mul_f32_e32 v35, v16, v174
	v_fma_f32 v34, -v17, v174, v34
	v_fma_f32 v35, v17, v173, v35
	v_add_u32_e32 v33, v32, v114
	v_cvt_pk_f16_f32 v16, v34, v35
	v_mul_f32_e32 v17, v18, v175
	v_mul_f32_e32 v34, v18, v176
	v_fma_f32 v17, -v19, v176, v17
	v_fma_f32 v34, v19, v175, v34
	s_nop 0
	v_cvt_pk_f16_f32 v17, v17, v34
	ds_write2_b32 v33, v16, v17 offset1:17
	v_mul_f32_e32 v16, v20, v177
	v_mul_f32_e32 v17, v20, v178
	v_fma_f32 v16, -v21, v178, v16
	v_fma_f32 v17, v21, v177, v17
	v_and_b32_e32 v20, 0xdf, v116
	v_cvt_pk_f16_f32 v16, v16, v17
	v_mul_f32_e32 v17, v22, v179
	v_mul_f32_e32 v18, v22, v180
	v_fma_f32 v17, -v23, v180, v17
	v_fma_f32 v18, v23, v179, v18
	s_nop 0
	v_cvt_pk_f16_f32 v17, v17, v18
	ds_write2_b32 v33, v16, v17 offset0:68 offset1:85
	v_mul_f32_e32 v16, v24, v181
	v_mul_f32_e32 v17, v24, v182
	v_fma_f32 v16, -v25, v182, v16
	v_fma_f32 v17, v25, v181, v17
	v_mad_i32_i24 v24, v119, s87, v118
	v_cvt_pk_f16_f32 v16, v16, v17
	v_mul_f32_e32 v17, v26, v183
	v_mul_f32_e32 v18, v26, v184
	v_fma_f32 v17, -v27, v184, v17
	v_fma_f32 v18, v27, v183, v18
	s_nop 0
	v_cvt_pk_f16_f32 v17, v17, v18
	ds_write2_b32 v33, v16, v17 offset0:136 offset1:153
	v_mul_f32_e32 v16, v28, v185
	v_mul_f32_e32 v17, v28, v186
	v_fma_f32 v16, -v29, v186, v16
	v_fma_f32 v17, v29, v185, v17
	s_nop 0
	v_cvt_pk_f16_f32 v16, v16, v17
	v_mul_f32_e32 v17, v30, v187
	v_mul_f32_e32 v18, v30, v188
	v_fma_f32 v17, -v31, v188, v17
	v_fma_f32 v18, v31, v187, v18
	s_nop 0
	v_cvt_pk_f16_f32 v17, v17, v18
	ds_write2_b32 v33, v16, v17 offset0:204 offset1:221
	v_add_u32_e32 v16, v32, v48
	v_mul_f32_e32 v17, v0, v189
	v_mul_f32_e32 v18, v0, v190
	v_fma_f32 v17, -v1, v190, v17
	v_fma_f32 v18, v1, v189, v18
	s_nop 0
	v_cvt_pk_f16_f32 v0, v17, v18
	v_mul_f32_e32 v1, v2, v191
	v_mul_f32_e32 v17, v2, v192
	v_fma_f32 v1, -v3, v192, v1
	v_fma_f32 v17, v3, v191, v17
	s_nop 0
	v_cvt_pk_f16_f32 v1, v1, v17
	ds_write2_b32 v16, v0, v1 offset1:17
	v_mul_f32_e32 v0, v4, v193
	v_mul_f32_e32 v1, v4, v194
	v_fma_f32 v0, -v5, v194, v0
	v_fma_f32 v1, v5, v193, v1
	s_nop 0
	v_cvt_pk_f16_f32 v0, v0, v1
	v_mul_f32_e32 v1, v6, v195
	v_mul_f32_e32 v2, v6, v196
	v_fma_f32 v1, -v7, v196, v1
	v_fma_f32 v2, v7, v195, v2
	s_nop 0
	v_cvt_pk_f16_f32 v1, v1, v2
	ds_write2_b32 v16, v0, v1 offset0:68 offset1:85
	v_mul_f32_e32 v0, v8, v197
	v_mul_f32_e32 v1, v8, v198
	v_fma_f32 v0, -v9, v198, v0
	v_fma_f32 v1, v9, v197, v1
	s_nop 0
	v_cvt_pk_f16_f32 v0, v0, v1
	v_mul_f32_e32 v1, v10, v199
	v_mul_f32_e32 v2, v10, v200
	v_fma_f32 v1, -v11, v200, v1
	v_fma_f32 v2, v11, v199, v2
	s_nop 0
	v_cvt_pk_f16_f32 v1, v1, v2
	ds_write2_b32 v16, v0, v1 offset0:136 offset1:153
	v_mul_f32_e32 v0, v12, v201
	v_mul_f32_e32 v1, v12, v202
	v_fma_f32 v0, -v13, v202, v0
	v_fma_f32 v1, v13, v201, v1
	s_nop 0
	v_cvt_pk_f16_f32 v0, v0, v1
	v_mul_f32_e32 v1, v14, v203
	v_mul_f32_e32 v2, v14, v204
	v_fma_f32 v1, -v15, v204, v1
	v_fma_f32 v2, v15, v203, v2
	s_nop 0
	v_cvt_pk_f16_f32 v1, v1, v2
	ds_write2_b32 v16, v0, v1 offset0:204 offset1:221
	v_lshrrev_b32_e32 v0, 4, v20
	v_add_lshl_u32 v116, v0, v20, 2
	v_add_u32_e32 v17, v24, v116
	s_waitcnt lgkmcnt(0)
	s_barrier
	ds_read_b32 v0, v17 offset:34816
	ds_read_b32 v1, v17 offset:36992
	ds_read_b32 v2, v17 offset:39168
	ds_read_b32 v3, v17 offset:41344
	ds_read_b32 v18, v17 offset:56576
	ds_read_b32 v19, v17 offset:58752
	ds_read_b32 v16, v17 offset:52224
	s_waitcnt lgkmcnt(3)
	v_mfma_f32_32x32x16_f16 v[0:15], v[76:79], v[0:3], 0
	ds_read_b32 v17, v17 offset:54400
	v_or_b32_e32 v20, 32, v20
	v_lshrrev_b32_e32 v21, 4, v20
	v_add_lshl_u32 v118, v21, v20, 2
	v_add_u32_e32 v21, v24, v118
	v_add_u32_e32 v24, 0x19800, v24
	v_add_u32_e32 v25, v24, v116
	s_waitcnt lgkmcnt(0)
	v_mfma_f32_32x32x16_f16 v[0:15], v[92:95], v[16:19], v[0:15]
	ds_read_b32 v16, v21 offset:34816
	ds_read_b32 v17, v21 offset:36992
	ds_read_b32 v18, v21 offset:39168
	ds_read_b32 v19, v21 offset:41344
	ds_read_b32 v22, v21 offset:56576
	ds_read_b32 v23, v21 offset:58752
	ds_read_b32 v20, v21 offset:52224
	ds_read_b32 v21, v21 offset:54400
	v_add_u32_e32 v113, v24, v118
	s_nop 2
	v_cvt_pk_f16_f32 v0, v0, v1
	s_waitcnt lgkmcnt(4)
	v_mfma_f32_32x32x16_f16 v[48:63], v[76:79], v[16:19], 0
	s_waitcnt lgkmcnt(0)
	v_mfma_f32_32x32x16_f16 v[48:63], v[92:95], v[20:23], v[48:63]
	ds_read_b32 v16, v25
	ds_read_b32 v17, v25 offset:2176
	ds_read_b32 v18, v25 offset:4352
	ds_read_b32 v19, v25 offset:6528
	ds_read_b32 v22, v25 offset:21760
	ds_read_b32 v23, v25 offset:23936
	ds_read_b32 v20, v25 offset:17408
	ds_read_b32 v21, v25 offset:19584
	s_nop 3
	v_cvt_pk_f16_f32 v1, v48, v49
	s_waitcnt lgkmcnt(4)
	v_mfma_f32_32x32x16_f16 v[32:47], v[76:79], v[16:19], 0
	ds_read_b32 v16, v113
	ds_read_b32 v17, v113 offset:2176
	ds_read_b32 v18, v113 offset:4352
	ds_read_b32 v19, v113 offset:6528
	ds_read_b32 v114, v113 offset:21760
	ds_read_b32 v115, v113 offset:23936
	ds_read_b32 v112, v113 offset:17408
	ds_read_b32 v113, v113 offset:19584
	s_waitcnt lgkmcnt(8)
	v_mfma_f32_32x32x16_f16 v[32:47], v[92:95], v[20:23], v[32:47]
	s_waitcnt lgkmcnt(4)
	v_mfma_f32_32x32x16_f16 v[16:31], v[76:79], v[16:19], 0
	s_waitcnt lgkmcnt(0)
	v_mfma_f32_32x32x16_f16 v[16:31], v[92:95], v[112:115], v[16:31]
	v_mul_i32_i24_e32 v112, 0x4400, v119
	v_mul_u32_u24_e32 v113, 0x880, v117
	v_add3_u32 v112, 0, v112, v113
	v_add_u32_e32 v113, v112, v116
	ds_write_b32 v113, v0
	v_cvt_pk_f16_f32 v0, v2, v3
	ds_write_b32 v113, v0 offset:1088
	v_cvt_pk_f16_f32 v0, v4, v5
	ds_write_b32 v113, v0 offset:4352
	v_cvt_pk_f16_f32 v0, v6, v7
	ds_write_b32 v113, v0 offset:5440
	v_cvt_pk_f16_f32 v0, v8, v9
	ds_write_b32 v113, v0 offset:8704
	v_cvt_pk_f16_f32 v0, v10, v11
	ds_write_b32 v113, v0 offset:9792
	v_cvt_pk_f16_f32 v0, v12, v13
	ds_write_b32 v113, v0 offset:13056
	v_cvt_pk_f16_f32 v0, v14, v15
	ds_write_b32 v113, v0 offset:14144
	v_add_u32_e32 v0, v112, v118
	ds_write_b32 v0, v1
	v_cvt_pk_f16_f32 v1, v50, v51
	ds_write_b32 v0, v1 offset:1088
	v_cvt_pk_f16_f32 v1, v52, v53
	ds_write_b32 v0, v1 offset:4352
	v_cvt_pk_f16_f32 v1, v54, v55
	ds_write_b32 v0, v1 offset:5440
	v_cvt_pk_f16_f32 v1, v56, v57
	ds_write_b32 v0, v1 offset:8704
	v_cvt_pk_f16_f32 v1, v58, v59
	ds_write_b32 v0, v1 offset:9792
	v_cvt_pk_f16_f32 v1, v60, v61
	ds_write_b32 v0, v1 offset:13056
	v_cvt_pk_f16_f32 v1, v62, v63
	ds_write_b32 v0, v1 offset:14144
	v_add_u32_e32 v0, 0x11000, v112
	v_add_u32_e32 v1, v0, v116
	v_cvt_pk_f16_f32 v2, v32, v33
	ds_write_b32 v1, v2
	v_cvt_pk_f16_f32 v2, v34, v35
	ds_write_b32 v1, v2 offset:1088
	v_cvt_pk_f16_f32 v2, v36, v37
	ds_write_b32 v1, v2 offset:4352
	v_cvt_pk_f16_f32 v2, v38, v39
	ds_write_b32 v1, v2 offset:5440
	v_cvt_pk_f16_f32 v2, v40, v41
	ds_write_b32 v1, v2 offset:8704
	v_cvt_pk_f16_f32 v2, v42, v43
	ds_write_b32 v1, v2 offset:9792
	v_cvt_pk_f16_f32 v2, v44, v45
	ds_write_b32 v1, v2 offset:13056
	v_cvt_pk_f16_f32 v2, v46, v47
	ds_write_b32 v1, v2 offset:14144
	v_add_u32_e32 v0, v0, v118
	v_cvt_pk_f16_f32 v1, v16, v17
	ds_write_b32 v0, v1
	v_cvt_pk_f16_f32 v1, v18, v19
	ds_write_b32 v0, v1 offset:1088
	v_cvt_pk_f16_f32 v1, v20, v21
	ds_write_b32 v0, v1 offset:4352
	v_cvt_pk_f16_f32 v1, v22, v23
	ds_write_b32 v0, v1 offset:5440
	v_cvt_pk_f16_f32 v1, v24, v25
	ds_write_b32 v0, v1 offset:8704
	v_cvt_pk_f16_f32 v1, v26, v27
	ds_write_b32 v0, v1 offset:9792
	v_cvt_pk_f16_f32 v1, v28, v29
	ds_write_b32 v0, v1 offset:13056
	v_cvt_pk_f16_f32 v1, v30, v31
	ds_write_b32 v0, v1 offset:14144
	v_lshl_add_u64 v[0:1], v[160:161], 0, s[6:7]
	s_waitcnt lgkmcnt(0)
	s_barrier
	global_load_dwordx4 v[124:127], v[0:1], off
	global_load_ushort v246, v[0:1], off offset:16
	global_load_ushort v245, v[0:1], off offset:-2
	v_cndmask_b32_e64 v0, 0, 1, s[52:53]
	v_mov_b32_e32 v112, 0
	v_cmp_ne_u32_e64 s[6:7], 1, v0
	s_cbranch_vccnz .LBB0_1798
	s_add_i32 s92, s8, s45
	s_ashr_i32 s93, s92, 31
	s_lshl_b64 s[92:93], s[92:93], 13
	v_lshl_add_u64 v[0:1], v[160:161], 0, s[92:93]
	global_load_dwordx4 v[120:123], v[0:1], off

.LBB0_1800:
	v_ashrrev_i32_e32 v0, 4, v130
	v_mul_u32_u24_e32 v4, 0x2200, v129
	v_add_lshl_u32 v6, v0, v130, 2
	v_add3_u32 v3, 0, v6, v4
	ds_read_b32 v0, v3
	ds_read_b32 v2, v3 offset:17408
	s_add_i32 s10, 0, 0x11000
	v_add3_u32 v6, s10, v6, v4
	s_add_i32 s92, s91, s8
	s_waitcnt lgkmcnt(1)
	v_cvt_f32_f16_e32 v1, v0
	v_cvt_f32_f16_sdwa v0, v0 dst_sel:DWORD dst_unused:UNUSED_PAD src0_sel:WORD_1
	s_waitcnt lgkmcnt(0)
	v_cvt_f32_f16_e32 v5, v2
	v_cvt_f32_f16_sdwa v2, v2 dst_sel:DWORD dst_unused:UNUSED_PAD src0_sel:WORD_1
	s_ashr_i32 s93, s92, 31
	s_lshl_b64 s[92:93], s[92:93], 13
	v_add_f32_e32 v7, v1, v5
	v_add_f32_e32 v8, v0, v2
	v_sub_f32_e32 v1, v1, v5
	v_sub_f32_e32 v0, v0, v2
	v_mul_f32_e32 v2, v7, v210
	v_mul_f32_e64 v5, -v7, v211
	v_fma_f32 v2, -v8, v211, v2
	v_fma_f32 v5, -v8, v210, v5
	v_mul_f32_e32 v7, v1, v212
	v_mul_f32_e64 v8, -v1, v213
	v_fma_f32 v7, -v0, v213, v7
	v_fma_f32 v8, -v0, v212, v8
	ds_read_b32 v1, v3 offset:2176
	v_cvt_pk_f16_f32 v0, v2, v5
	ds_read_b32 v5, v3 offset:19584
	v_cvt_pk_f16_f32 v16, v7, v8
	s_and_b64 vcc, exec, s[6:7]
	s_waitcnt lgkmcnt(1)
	v_cvt_f32_f16_e32 v2, v1
	v_cvt_f32_f16_sdwa v1, v1 dst_sel:DWORD dst_unused:UNUSED_PAD src0_sel:WORD_1
	s_waitcnt lgkmcnt(0)
	v_cvt_f32_f16_e32 v7, v5
	v_cvt_f32_f16_sdwa v5, v5 dst_sel:DWORD dst_unused:UNUSED_PAD src0_sel:WORD_1
	v_add_f32_e32 v8, v2, v7
	v_add_f32_e32 v9, v1, v5
	v_sub_f32_e32 v2, v2, v7
	v_sub_f32_e32 v1, v1, v5
	v_mul_f32_e32 v5, v8, v214
	v_mul_f32_e64 v7, -v8, v215
	v_fma_f32 v5, -v9, v215, v5
	v_fma_f32 v7, -v9, v214, v7
	v_mul_f32_e32 v8, v2, v216
	v_mul_f32_e64 v9, -v2, v217
	v_fma_f32 v8, -v1, v217, v8
	v_fma_f32 v9, -v1, v216, v9
	ds_read_b32 v2, v3 offset:4352
	v_cvt_pk_f16_f32 v1, v5, v7
	ds_read_b32 v7, v3 offset:21760
	v_cvt_pk_f16_f32 v17, v8, v9
	s_waitcnt lgkmcnt(1)
	v_cvt_f32_f16_e32 v5, v2
	v_cvt_f32_f16_sdwa v2, v2 dst_sel:DWORD dst_unused:UNUSED_PAD src0_sel:WORD_1
	s_waitcnt lgkmcnt(0)
	v_cvt_f32_f16_e32 v8, v7
	v_cvt_f32_f16_sdwa v7, v7 dst_sel:DWORD dst_unused:UNUSED_PAD src0_sel:WORD_1
	v_add_f32_e32 v9, v5, v8
	v_add_f32_e32 v10, v2, v7
	v_sub_f32_e32 v5, v5, v8
	v_sub_f32_e32 v2, v2, v7
	v_mul_f32_e32 v7, v9, v218
	v_mul_f32_e64 v8, -v9, v219
	v_fma_f32 v7, -v10, v219, v7
	v_fma_f32 v8, -v10, v218, v8
	v_mul_f32_e32 v9, v5, v220
	v_mul_f32_e64 v10, -v5, v221
	v_fma_f32 v9, -v2, v221, v9
	v_fma_f32 v10, -v2, v220, v10
	ds_read_b32 v5, v3 offset:6528
	ds_read_b32 v3, v3 offset:23936
	v_cvt_pk_f16_f32 v2, v7, v8
	v_cvt_pk_f16_f32 v18, v9, v10
	s_waitcnt lgkmcnt(1)
	v_cvt_f32_f16_e32 v7, v5
	v_cvt_f32_f16_sdwa v5, v5 dst_sel:DWORD dst_unused:UNUSED_PAD src0_sel:WORD_1
	s_waitcnt lgkmcnt(0)
	v_cvt_f32_f16_e32 v8, v3
	v_cvt_f32_f16_sdwa v3, v3 dst_sel:DWORD dst_unused:UNUSED_PAD src0_sel:WORD_1
	v_add_f32_e32 v9, v7, v8
	v_add_f32_e32 v10, v5, v3
	v_sub_f32_e32 v7, v7, v8
	v_sub_f32_e32 v3, v5, v3
	v_mul_f32_e32 v5, v9, v222
	v_mul_f32_e64 v8, -v9, v223
	v_fma_f32 v5, -v10, v223, v5
	v_fma_f32 v8, -v10, v222, v8
	v_mul_f32_e32 v9, v7, v224
	v_mul_f32_e64 v10, -v7, v225
	v_fma_f32 v9, -v3, v225, v9
	v_fma_f32 v10, -v3, v224, v10
	s_nop 0
	v_cvt_pk_f16_f32 v3, v5, v8
	v_ashrrev_i32_e32 v5, 4, v128
	v_add_lshl_u32 v5, v5, v128, 2
	v_add3_u32 v7, 0, v5, v4
	v_cvt_pk_f16_f32 v19, v9, v10
	ds_read_b32 v8, v7
	ds_read_b32 v10, v7 offset:17408
	v_add3_u32 v4, s10, v5, v4
	ds_read_b32 v5, v4
	s_waitcnt lgkmcnt(2)
	v_cvt_f32_f16_e32 v9, v8
	v_cvt_f32_f16_sdwa v8, v8 dst_sel:DWORD dst_unused:UNUSED_PAD src0_sel:WORD_1
	s_waitcnt lgkmcnt(1)
	v_cvt_f32_f16_e32 v11, v10
	v_cvt_f32_f16_sdwa v10, v10 dst_sel:DWORD dst_unused:UNUSED_PAD src0_sel:WORD_1
	v_add_f32_e32 v12, v9, v11
	v_add_f32_e32 v13, v8, v10
	v_sub_f32_e32 v9, v9, v11
	v_sub_f32_e32 v8, v8, v10
	v_mul_f32_e32 v10, v12, v226
	v_mul_f32_e64 v11, -v12, v227
	v_fma_f32 v10, -v13, v227, v10
	v_fma_f32 v11, -v13, v226, v11
	v_mul_f32_e32 v12, v9, v228
	v_mul_f32_e64 v13, -v9, v229
	v_fma_f32 v12, -v8, v229, v12
	v_fma_f32 v13, -v8, v228, v13
	ds_read_b32 v8, v7 offset:2176
	v_cvt_pk_f16_f32 v20, v10, v11
	ds_read_b32 v10, v7 offset:19584
	v_cvt_pk_f16_f32 v32, v12, v13
	s_waitcnt lgkmcnt(1)
	v_cvt_f32_f16_e32 v9, v8
	v_cvt_f32_f16_sdwa v8, v8 dst_sel:DWORD dst_unused:UNUSED_PAD src0_sel:WORD_1
	s_waitcnt lgkmcnt(0)
	v_cvt_f32_f16_e32 v11, v10
	v_cvt_f32_f16_sdwa v10, v10 dst_sel:DWORD dst_unused:UNUSED_PAD src0_sel:WORD_1
	v_add_f32_e32 v12, v9, v11
	v_add_f32_e32 v13, v8, v10
	v_sub_f32_e32 v9, v9, v11
	v_sub_f32_e32 v8, v8, v10
	v_mul_f32_e32 v10, v12, v230
	v_mul_f32_e64 v11, -v12, v231
	v_fma_f32 v10, -v13, v231, v10
	v_fma_f32 v11, -v13, v230, v11
	v_mul_f32_e32 v12, v9, v232
	v_mul_f32_e64 v13, -v9, v233
	v_fma_f32 v12, -v8, v233, v12
	v_fma_f32 v13, -v8, v232, v13
	ds_read_b32 v8, v7 offset:4352
	v_cvt_pk_f16_f32 v21, v10, v11
	ds_read_b32 v10, v7 offset:21760
	v_cvt_pk_f16_f32 v33, v12, v13
	s_waitcnt lgkmcnt(1)
	v_cvt_f32_f16_e32 v9, v8
	v_cvt_f32_f16_sdwa v8, v8 dst_sel:DWORD dst_unused:UNUSED_PAD src0_sel:WORD_1
	s_waitcnt lgkmcnt(0)
	v_cvt_f32_f16_e32 v11, v10
	v_cvt_f32_f16_sdwa v10, v10 dst_sel:DWORD dst_unused:UNUSED_PAD src0_sel:WORD_1
	v_add_f32_e32 v12, v9, v11
	v_add_f32_e32 v13, v8, v10
	v_sub_f32_e32 v8, v8, v10
	v_sub_f32_e32 v9, v9, v11
	v_mul_f32_e32 v10, v12, v234
	v_mul_f32_e64 v11, -v12, v235
	v_fma_f32 v10, -v13, v235, v10
	v_fma_f32 v11, -v13, v234, v11
	v_mul_f32_e32 v12, v9, v236
	v_mul_f32_e64 v13, -v9, v237
	v_fma_f32 v12, -v8, v237, v12
	v_fma_f32 v13, -v8, v236, v13
	ds_read_b32 v8, v7 offset:6528
	ds_read_b32 v7, v7 offset:23936
	v_cvt_pk_f16_f32 v22, v10, v11
	v_cvt_pk_f16_f32 v34, v12, v13
	s_waitcnt lgkmcnt(1)
	v_cvt_f32_f16_e32 v9, v8
	v_cvt_f32_f16_sdwa v8, v8 dst_sel:DWORD dst_unused:UNUSED_PAD src0_sel:WORD_1
	s_waitcnt lgkmcnt(0)
	v_cvt_f32_f16_e32 v10, v7
	v_cvt_f32_f16_sdwa v7, v7 dst_sel:DWORD dst_unused:UNUSED_PAD src0_sel:WORD_1
	v_add_f32_e32 v11, v9, v10
	v_add_f32_e32 v12, v8, v7
	v_sub_f32_e32 v9, v9, v10
	v_sub_f32_e32 v7, v8, v7
	v_mul_f32_e32 v8, v11, v238
	v_mul_f32_e64 v10, -v11, v239
	v_fma_f32 v8, -v12, v239, v8
	v_fma_f32 v10, -v12, v238, v10
	v_mul_f32_e32 v11, v9, v240
	v_mul_f32_e64 v12, -v9, v241
	v_fma_f32 v11, -v7, v241, v11
	v_fma_f32 v12, -v7, v240, v12
	ds_read_b32 v7, v6
	ds_read_b32 v9, v6 offset:17408
	v_cvt_pk_f16_f32 v23, v8, v10
	v_cvt_pk_f16_f32 v35, v11, v12
	s_waitcnt lgkmcnt(1)
	v_cvt_f32_f16_e32 v8, v7
	v_cvt_f32_f16_sdwa v7, v7 dst_sel:DWORD dst_unused:UNUSED_PAD src0_sel:WORD_1
	s_waitcnt lgkmcnt(0)
	v_cvt_f32_f16_e32 v10, v9
	v_cvt_f32_f16_sdwa v9, v9 dst_sel:DWORD dst_unused:UNUSED_PAD src0_sel:WORD_1
	v_add_f32_e32 v11, v8, v10
	v_add_f32_e32 v12, v7, v9
	v_sub_f32_e32 v8, v8, v10
	v_sub_f32_e32 v7, v7, v9
	v_mul_f32_e32 v9, v11, v210
	v_mul_f32_e64 v10, -v11, v211
	v_fma_f32 v9, -v12, v211, v9
	v_fma_f32 v10, -v12, v210, v10
	v_mul_f32_e32 v11, v8, v212
	v_mul_f32_e64 v12, -v8, v213
	v_fma_f32 v11, -v7, v213, v11
	v_fma_f32 v12, -v7, v212, v12
	ds_read_b32 v7, v6 offset:2176
	v_cvt_pk_f16_f32 v36, v9, v10
	ds_read_b32 v9, v6 offset:19584
	v_cvt_pk_f16_f32 v48, v11, v12
	s_waitcnt lgkmcnt(1)
	v_cvt_f32_f16_e32 v8, v7
	v_cvt_f32_f16_sdwa v7, v7 dst_sel:DWORD dst_unused:UNUSED_PAD src0_sel:WORD_1
	s_waitcnt lgkmcnt(0)
	v_cvt_f32_f16_e32 v10, v9
	v_cvt_f32_f16_sdwa v9, v9 dst_sel:DWORD dst_unused:UNUSED_PAD src0_sel:WORD_1
	v_add_f32_e32 v11, v8, v10
	v_add_f32_e32 v12, v7, v9
	v_sub_f32_e32 v8, v8, v10
	v_sub_f32_e32 v7, v7, v9
	v_mul_f32_e32 v9, v11, v214
	v_mul_f32_e64 v10, -v11, v215
	v_fma_f32 v9, -v12, v215, v9
	v_fma_f32 v10, -v12, v214, v10
	v_mul_f32_e32 v11, v8, v216
	v_mul_f32_e64 v12, -v8, v217
	v_fma_f32 v11, -v7, v217, v11
	v_fma_f32 v12, -v7, v216, v12
	ds_read_b32 v7, v6 offset:4352
	v_cvt_pk_f16_f32 v37, v9, v10
	ds_read_b32 v9, v6 offset:21760
	v_cvt_pk_f16_f32 v49, v11, v12
	s_waitcnt lgkmcnt(1)
	v_cvt_f32_f16_e32 v8, v7
	v_cvt_f32_f16_sdwa v7, v7 dst_sel:DWORD dst_unused:UNUSED_PAD src0_sel:WORD_1
	s_waitcnt lgkmcnt(0)
	v_cvt_f32_f16_e32 v10, v9
	v_cvt_f32_f16_sdwa v9, v9 dst_sel:DWORD dst_unused:UNUSED_PAD src0_sel:WORD_1
	v_add_f32_e32 v11, v8, v10
	v_add_f32_e32 v12, v7, v9
	v_sub_f32_e32 v7, v7, v9
	v_sub_f32_e32 v8, v8, v10
	v_mul_f32_e32 v9, v11, v218
	v_mul_f32_e64 v10, -v11, v219
	v_fma_f32 v9, -v12, v219, v9
	v_fma_f32 v10, -v12, v218, v10
	v_mul_f32_e32 v11, v8, v220
	v_mul_f32_e64 v12, -v8, v221
	v_fma_f32 v11, -v7, v221, v11
	v_fma_f32 v12, -v7, v220, v12
	ds_read_b32 v7, v6 offset:6528
	ds_read_b32 v6, v6 offset:23936
	v_cvt_pk_f16_f32 v38, v9, v10
	v_cvt_pk_f16_f32 v50, v11, v12
	s_waitcnt lgkmcnt(1)
	v_cvt_f32_f16_e32 v8, v7
	v_cvt_f32_f16_sdwa v7, v7 dst_sel:DWORD dst_unused:UNUSED_PAD src0_sel:WORD_1
	s_waitcnt lgkmcnt(0)
	v_cvt_f32_f16_e32 v9, v6
	v_cvt_f32_f16_sdwa v6, v6 dst_sel:DWORD dst_unused:UNUSED_PAD src0_sel:WORD_1
	v_add_f32_e32 v10, v8, v9
	v_add_f32_e32 v11, v7, v6
	v_sub_f32_e32 v8, v8, v9
	v_sub_f32_e32 v6, v7, v6
	v_mul_f32_e32 v7, v10, v222
	v_mul_f32_e64 v9, -v10, v223
	v_fma_f32 v7, -v11, v223, v7
	v_fma_f32 v9, -v11, v222, v9
	v_mul_f32_e32 v10, v8, v224
	v_mul_f32_e64 v11, -v8, v225
	v_fma_f32 v10, -v6, v225, v10
	v_fma_f32 v11, -v6, v224, v11
	s_nop 0
	v_cvt_pk_f16_f32 v39, v7, v9
	ds_read_b32 v7, v4 offset:17408
	v_cvt_f32_f16_e32 v6, v5
	v_cvt_f32_f16_sdwa v5, v5 dst_sel:DWORD dst_unused:UNUSED_PAD src0_sel:WORD_1
	v_cvt_pk_f16_f32 v51, v10, v11
	s_waitcnt lgkmcnt(0)
	v_cvt_f32_f16_e32 v8, v7
	v_cvt_f32_f16_sdwa v7, v7 dst_sel:DWORD dst_unused:UNUSED_PAD src0_sel:WORD_1
	v_add_f32_e32 v9, v6, v8
	v_add_f32_e32 v10, v5, v7
	v_sub_f32_e32 v6, v6, v8
	v_sub_f32_e32 v5, v5, v7
	v_mul_f32_e32 v7, v9, v226
	v_mul_f32_e64 v8, -v9, v227
	v_fma_f32 v7, -v10, v227, v7
	v_fma_f32 v8, -v10, v226, v8
	v_mul_f32_e32 v9, v6, v228
	v_mul_f32_e64 v10, -v6, v229
	v_fma_f32 v9, -v5, v229, v9
	v_fma_f32 v10, -v5, v228, v10
	ds_read_b32 v5, v4 offset:2176
	v_cvt_pk_f16_f32 v52, v7, v8
	ds_read_b32 v7, v4 offset:19584
	v_cvt_pk_f16_f32 v128, v9, v10
	s_waitcnt lgkmcnt(1)
	v_cvt_f32_f16_e32 v6, v5
	v_cvt_f32_f16_sdwa v5, v5 dst_sel:DWORD dst_unused:UNUSED_PAD src0_sel:WORD_1
	s_waitcnt lgkmcnt(0)
	v_cvt_f32_f16_e32 v8, v7
	v_cvt_f32_f16_sdwa v7, v7 dst_sel:DWORD dst_unused:UNUSED_PAD src0_sel:WORD_1
	v_add_f32_e32 v9, v6, v8
	v_add_f32_e32 v10, v5, v7
	v_sub_f32_e32 v6, v6, v8
	v_sub_f32_e32 v5, v5, v7
	v_mul_f32_e32 v7, v9, v230
	v_mul_f32_e64 v8, -v9, v231
	v_fma_f32 v7, -v10, v231, v7
	v_fma_f32 v8, -v10, v230, v8
	v_mul_f32_e32 v9, v6, v232
	v_mul_f32_e64 v10, -v6, v233
	v_fma_f32 v9, -v5, v233, v9
	v_fma_f32 v10, -v5, v232, v10
	ds_read_b32 v5, v4 offset:4352
	v_cvt_pk_f16_f32 v53, v7, v8
	ds_read_b32 v7, v4 offset:21760
	v_cvt_pk_f16_f32 v129, v9, v10
	s_waitcnt lgkmcnt(1)
	v_cvt_f32_f16_e32 v6, v5
	v_cvt_f32_f16_sdwa v5, v5 dst_sel:DWORD dst_unused:UNUSED_PAD src0_sel:WORD_1
	s_waitcnt lgkmcnt(0)
	v_cvt_f32_f16_e32 v8, v7
	v_cvt_f32_f16_sdwa v7, v7 dst_sel:DWORD dst_unused:UNUSED_PAD src0_sel:WORD_1
	v_add_f32_e32 v9, v6, v8
	v_add_f32_e32 v10, v5, v7
	v_sub_f32_e32 v5, v5, v7
	v_sub_f32_e32 v6, v6, v8
	v_mul_f32_e32 v7, v9, v234
	v_mul_f32_e64 v8, -v9, v235
	v_fma_f32 v7, -v10, v235, v7
	v_fma_f32 v8, -v10, v234, v8
	v_mul_f32_e32 v9, v6, v236
	v_mul_f32_e64 v10, -v6, v237
	v_fma_f32 v9, -v5, v237, v9
	v_fma_f32 v10, -v5, v236, v10
	ds_read_b32 v5, v4 offset:6528
	ds_read_b32 v4, v4 offset:23936
	v_cvt_pk_f16_f32 v54, v7, v8
	v_cvt_pk_f16_f32 v130, v9, v10
	s_waitcnt lgkmcnt(1)
	v_cvt_f32_f16_e32 v6, v5
	v_cvt_f32_f16_sdwa v5, v5 dst_sel:DWORD dst_unused:UNUSED_PAD src0_sel:WORD_1
	s_waitcnt lgkmcnt(0)
	v_cvt_f32_f16_e32 v7, v4
	v_cvt_f32_f16_sdwa v4, v4 dst_sel:DWORD dst_unused:UNUSED_PAD src0_sel:WORD_1
	v_add_f32_e32 v8, v6, v7
	v_add_f32_e32 v9, v5, v4
	v_sub_f32_e32 v6, v6, v7
	v_sub_f32_e32 v4, v5, v4
	v_mul_f32_e32 v5, v8, v238
	v_mul_f32_e64 v7, -v8, v239
	v_fma_f32 v5, -v9, v239, v5
	v_fma_f32 v7, -v9, v238, v7
	v_mul_f32_e32 v8, v6, v240
	v_mul_f32_e64 v9, -v6, v241
	v_fma_f32 v8, -v4, v241, v8
	v_fma_f32 v9, -v4, v240, v9
	s_nop 0
	v_cvt_pk_f16_f32 v55, v5, v7
	v_cvt_pk_f16_f32 v131, v8, v9
	v_mfma_f32_32x32x16_f16 v[0:15], v[68:71], v[0:3], 0
	v_mfma_f32_32x32x16_f16 v[0:15], v[84:87], v[16:19], v[0:15]
	v_mfma_f32_32x32x16_f16 v[16:31], v[72:75], v[20:23], 0
	s_nop 10
	v_cvt_pk_f16_f32 v0, v0, v1
	v_add_u32_e32 v1, 0x8800, v251
	v_cvt_pk_f16_f32 v2, v2, v3
	ds_write2_b32 v1, v0, v2 offset1:1
	v_cvt_pk_f16_f32 v0, v4, v5
	v_add_u32_e32 v1, 0x8810, v251
	v_cvt_pk_f16_f32 v2, v6, v7
	v_mfma_f32_32x32x16_f16 v[16:31], v[88:91], v[32:35], v[16:31]
	ds_write2_b32 v1, v0, v2 offset1:1
	v_cvt_pk_f16_f32 v0, v8, v9
	v_add_u32_e32 v1, 0x8820, v251
	v_cvt_pk_f16_f32 v2, v10, v11
	ds_write2_b32 v1, v0, v2 offset1:1
	v_cvt_pk_f16_f32 v0, v12, v13
	v_add_u32_e32 v1, 0x8830, v251
	v_mfma_f32_32x32x16_f16 v[32:47], v[68:71], v[36:39], 0
	v_cvt_pk_f16_f32 v2, v14, v15
	ds_write2_b32 v1, v0, v2 offset1:1
	s_nop 1
	v_cvt_pk_f16_f32 v0, v16, v17
	v_add_u32_e32 v1, 0x8800, v250
	v_cvt_pk_f16_f32 v2, v18, v19
	ds_write2_b32 v1, v0, v2 offset1:1
	v_cvt_pk_f16_f32 v0, v20, v21
	v_mfma_f32_32x32x16_f16 v[32:47], v[84:87], v[48:51], v[32:47]
	v_add_u32_e32 v1, 0x8810, v250
	v_cvt_pk_f16_f32 v2, v22, v23
	ds_write2_b32 v1, v0, v2 offset1:1
	v_cvt_pk_f16_f32 v0, v24, v25
	v_add_u32_e32 v1, 0x8820, v250
	v_cvt_pk_f16_f32 v2, v26, v27
	ds_write2_b32 v1, v0, v2 offset1:1
	v_mfma_f32_32x32x16_f16 v[48:63], v[72:75], v[52:55], 0
	v_cvt_pk_f16_f32 v0, v28, v29
	v_add_u32_e32 v1, 0x8830, v250
	v_cvt_pk_f16_f32 v2, v30, v31
	ds_write2_b32 v1, v0, v2 offset1:1
	v_add_u32_e32 v0, 0x19800, v247
	v_add_u32_e32 v1, v0, v248
	v_cvt_pk_f16_f32 v2, v32, v33
	v_mfma_f32_32x32x16_f16 v[48:63], v[88:91], v[128:131], v[48:63]
	v_cvt_pk_f16_f32 v3, v34, v35
	ds_write2_b32 v1, v2, v3 offset1:1
	v_cvt_pk_f16_f32 v2, v36, v37
	v_cvt_pk_f16_f32 v3, v38, v39
	ds_write2_b32 v1, v2, v3 offset0:4 offset1:5
	v_cvt_pk_f16_f32 v2, v40, v41
	v_cvt_pk_f16_f32 v3, v42, v43
	ds_write2_b32 v1, v2, v3 offset0:8 offset1:9
	v_cvt_pk_f16_f32 v2, v44, v45
	v_cvt_pk_f16_f32 v3, v46, v47
	ds_write2_b32 v1, v2, v3 offset0:12 offset1:13
	v_add_u32_e32 v0, v0, v249
	v_cvt_pk_f16_f32 v1, v48, v49
	v_cvt_pk_f16_f32 v2, v50, v51
	ds_write2_b32 v0, v1, v2 offset1:1
	v_cvt_pk_f16_f32 v1, v52, v53
	v_cvt_pk_f16_f32 v2, v54, v55
	ds_write2_b32 v0, v1, v2 offset0:4 offset1:5
	v_cvt_pk_f16_f32 v1, v56, v57
	v_cvt_pk_f16_f32 v2, v58, v59
	ds_write2_b32 v0, v1, v2 offset0:8 offset1:9
	v_cvt_pk_f16_f32 v1, v60, v61
	v_cvt_pk_f16_f32 v2, v62, v63
	v_mov_b32_e32 v248, v209
	ds_write2_b32 v0, v1, v2 offset0:12 offset1:13
	s_waitcnt lgkmcnt(0)
	s_barrier
	s_nop 0
	v_and_b32_e32 v0, 0xffffffdf, v248
	v_bfe_u32 v247, v248, 5, 1
	v_ashrrev_i32_e32 v249, 4, v0
	v_mad_u32_u24 v12, v247, s84, 0
	v_add_lshl_u32 v13, v249, v0, 2
	v_add_u32_e32 v7, v12, v13
	ds_read_b32 v0, v7 offset:34816
	ds_read_b32 v4, v7 offset:52224
	ds_read_b32 v1, v7 offset:36992
	ds_read_b32 v5, v7 offset:54400
	ds_read_b32 v2, v7 offset:39168
	ds_read_b32 v6, v7 offset:56576
	ds_read_b32 v3, v7 offset:41344
	ds_read_b32 v7, v7 offset:58752
	v_or_b32_e32 v8, 32, v248
	s_waitcnt lgkmcnt(1)
	v_mfma_f32_32x32x16_f16 v[48:63], v[64:67], v[0:3], 0
	v_ashrrev_i32_e32 v250, 4, v8
	v_add_lshl_u32 v14, v250, v8, 2
	v_add_u32_e32 v15, v12, v14
	ds_read_b32 v8, v15 offset:34816
	ds_read_b32 v20, v15 offset:52224
	ds_read_b32 v9, v15 offset:36992
	ds_read_b32 v21, v15 offset:54400
	ds_read_b32 v10, v15 offset:39168
	ds_read_b32 v22, v15 offset:56576
	ds_read_b32 v11, v15 offset:41344
	ds_read_b32 v23, v15 offset:58752
	v_add_u32_e32 v12, 0x19800, v12
	v_add_u32_e32 v13, v12, v13
	v_add_u32_e32 v12, v12, v14
	ds_read_b32 v16, v13
	ds_read_b32 v36, v13 offset:17408
	ds_read_b32 v17, v13 offset:2176
	ds_read_b32 v37, v13 offset:19584
	ds_read_b32 v18, v13 offset:4352
	ds_read_b32 v38, v13 offset:21760
	ds_read_b32 v19, v13 offset:6528
	ds_read_b32 v39, v13 offset:23936
	ds_read_b32 v32, v12
	ds_read_b32 v128, v12 offset:17408
	ds_read_b32 v33, v12 offset:2176
	ds_read_b32 v129, v12 offset:19584
	ds_read_b32 v34, v12 offset:4352
	ds_read_b32 v130, v12 offset:21760
	ds_read_b32 v35, v12 offset:6528
	ds_read_b32 v131, v12 offset:23936
	s_waitcnt lgkmcnt(14)
	v_mfma_f32_32x32x16_f16 v[48:63], v[80:83], v[4:7], v[48:63]
	s_nop 3
	v_mfma_f32_32x32x16_f16 v[0:15], v[64:67], v[8:11], 0
	v_mfma_f32_32x32x16_f16 v[0:15], v[80:83], v[20:23], v[0:15]
	s_waitcnt lgkmcnt(9)
	v_mfma_f32_32x32x16_f16 v[16:31], v[64:67], v[16:19], 0
	s_waitcnt lgkmcnt(8)
	v_mfma_f32_32x32x16_f16 v[16:31], v[80:83], v[36:39], v[16:31]
	s_waitcnt lgkmcnt(1)
	v_mfma_f32_32x32x16_f16 v[32:47], v[64:67], v[32:35], 0
	s_waitcnt lgkmcnt(0)
	v_mfma_f32_32x32x16_f16 v[32:47], v[80:83], v[128:131], v[32:47]
	v_and_b32_e32 v128, 15, v248
	v_mul_lo_u32 v130, v249, s86
	v_or_b32_e32 v130, v130, v128
	v_mul_f32_e32 v249, v48, v173
	v_mul_f32_e32 v251, v48, v174
	v_fma_f32 v249, -v49, v174, v249
	v_fma_f32 v251, v49, v173, v251
	v_mad_u32_u24 v129, v247, s89, 0
	v_lshlrev_b32_e32 v130, 2, v130
	v_cvt_pk_f16_f32 v48, v249, v251
	v_mul_f32_e32 v49, v50, v175
	v_mul_f32_e32 v249, v50, v176
	v_fma_f32 v49, -v51, v176, v49
	v_fma_f32 v249, v51, v175, v249
	v_add_u32_e32 v131, v129, v130
	v_cvt_pk_f16_f32 v49, v49, v249
	ds_write2_b32 v131, v48, v49 offset1:17
	v_mul_f32_e32 v48, v52, v177
	v_mul_f32_e32 v49, v52, v178
	v_fma_f32 v48, -v53, v178, v48
	v_fma_f32 v49, v53, v177, v49
	v_ashrrev_i32_e32 v249, 8, v248
	v_cvt_pk_f16_f32 v48, v48, v49
	v_mul_f32_e32 v49, v54, v179
	v_mul_f32_e32 v50, v54, v180
	v_fma_f32 v49, -v55, v180, v49
	v_fma_f32 v50, v55, v179, v50
	s_nop 0
	v_cvt_pk_f16_f32 v49, v49, v50
	ds_write2_b32 v131, v48, v49 offset0:68 offset1:85
	v_mul_f32_e32 v48, v56, v181
	v_mul_f32_e32 v49, v56, v182
	v_fma_f32 v48, -v57, v182, v48
	v_fma_f32 v49, v57, v181, v49
	s_nop 0
	v_cvt_pk_f16_f32 v48, v48, v49
	v_mul_f32_e32 v49, v58, v183
	v_mul_f32_e32 v50, v58, v184
	v_fma_f32 v49, -v59, v184, v49
	v_fma_f32 v50, v59, v183, v50
	s_nop 0
	v_cvt_pk_f16_f32 v49, v49, v50
	ds_write2_b32 v131, v48, v49 offset0:136 offset1:153
	v_mul_f32_e32 v48, v60, v185
	v_mul_f32_e32 v49, v60, v186
	v_fma_f32 v48, -v61, v186, v48
	v_fma_f32 v49, v61, v185, v49
	s_nop 0
	v_cvt_pk_f16_f32 v48, v48, v49
	v_mul_f32_e32 v49, v62, v187
	v_mul_f32_e32 v50, v62, v188
	v_fma_f32 v49, -v63, v188, v49
	v_fma_f32 v50, v63, v187, v50
	s_nop 0
	v_cvt_pk_f16_f32 v49, v49, v50
	ds_write2_b32 v131, v48, v49 offset0:204 offset1:221
	v_mul_lo_u32 v48, v250, s86
	v_or_b32_e32 v48, v48, v128
	v_lshlrev_b32_e32 v48, 2, v48
	v_mul_f32_e32 v50, v0, v189
	v_mul_f32_e32 v51, v0, v190
	v_fma_f32 v50, -v1, v190, v50
	v_fma_f32 v51, v1, v189, v51
	v_add_u32_e32 v49, v129, v48
	v_cvt_pk_f16_f32 v0, v50, v51
	v_mul_f32_e32 v1, v2, v191
	v_mul_f32_e32 v50, v2, v192
	v_fma_f32 v1, -v3, v192, v1
	v_fma_f32 v50, v3, v191, v50
	s_nop 0
	v_cvt_pk_f16_f32 v1, v1, v50
	ds_write2_b32 v49, v0, v1 offset1:17
	v_mul_f32_e32 v0, v4, v193
	v_mul_f32_e32 v1, v4, v194
	v_fma_f32 v0, -v5, v194, v0
	v_fma_f32 v1, v5, v193, v1
	s_nop 0
	v_cvt_pk_f16_f32 v0, v0, v1
	v_mul_f32_e32 v1, v6, v195
	v_mul_f32_e32 v2, v6, v196
	v_fma_f32 v1, -v7, v196, v1
	v_fma_f32 v2, v7, v195, v2
	s_nop 0
	v_cvt_pk_f16_f32 v1, v1, v2
	ds_write2_b32 v49, v0, v1 offset0:68 offset1:85
	v_mul_f32_e32 v0, v8, v197
	v_mul_f32_e32 v1, v8, v198
	v_fma_f32 v0, -v9, v198, v0
	v_fma_f32 v1, v9, v197, v1
	s_nop 0
	v_cvt_pk_f16_f32 v0, v0, v1
	v_mul_f32_e32 v1, v10, v199
	v_mul_f32_e32 v2, v10, v200
	v_fma_f32 v1, -v11, v200, v1
	v_fma_f32 v2, v11, v199, v2
	s_nop 0
	v_cvt_pk_f16_f32 v1, v1, v2
	ds_write2_b32 v49, v0, v1 offset0:136 offset1:153
	v_mul_f32_e32 v0, v12, v201
	v_mul_f32_e32 v1, v12, v202
	v_fma_f32 v0, -v13, v202, v0
	v_fma_f32 v1, v13, v201, v1
	s_nop 0
	v_cvt_pk_f16_f32 v0, v0, v1
	v_mul_f32_e32 v1, v14, v203
	v_mul_f32_e32 v2, v14, v204
	v_fma_f32 v1, -v15, v204, v1
	v_fma_f32 v2, v15, v203, v2
	s_nop 0
	v_cvt_pk_f16_f32 v1, v1, v2
	ds_write2_b32 v49, v0, v1 offset0:204 offset1:221
	v_add_u32_e32 v0, 0x11000, v129
	v_mul_f32_e32 v2, v16, v173
	v_mul_f32_e32 v3, v16, v174
	v_fma_f32 v2, -v17, v174, v2
	v_fma_f32 v3, v17, v173, v3
	v_add_u32_e32 v1, v0, v130
	v_cvt_pk_f16_f32 v2, v2, v3
	v_mul_f32_e32 v3, v18, v175
	v_mul_f32_e32 v4, v18, v176
	v_fma_f32 v3, -v19, v176, v3
	v_fma_f32 v4, v19, v175, v4
	v_add_u32_e32 v0, v0, v48
	v_cvt_pk_f16_f32 v3, v3, v4
	ds_write2_b32 v1, v2, v3 offset1:17
	v_mul_f32_e32 v2, v20, v177
	v_mul_f32_e32 v3, v20, v178
	v_fma_f32 v2, -v21, v178, v2
	v_fma_f32 v3, v21, v177, v3
	s_nop 0
	v_cvt_pk_f16_f32 v2, v2, v3
	v_mul_f32_e32 v3, v22, v179
	v_mul_f32_e32 v4, v22, v180
	v_fma_f32 v3, -v23, v180, v3
	v_fma_f32 v4, v23, v179, v4
	s_nop 0
	v_cvt_pk_f16_f32 v3, v3, v4
	ds_write2_b32 v1, v2, v3 offset0:68 offset1:85
	v_mul_f32_e32 v2, v24, v181
	v_mul_f32_e32 v3, v24, v182
	v_fma_f32 v2, -v25, v182, v2
	v_fma_f32 v3, v25, v181, v3
	s_nop 0
	v_cvt_pk_f16_f32 v2, v2, v3
	v_mul_f32_e32 v3, v26, v183
	v_mul_f32_e32 v4, v26, v184
	v_fma_f32 v3, -v27, v184, v3
	v_fma_f32 v4, v27, v183, v4
	s_nop 0
	v_cvt_pk_f16_f32 v3, v3, v4
	ds_write2_b32 v1, v2, v3 offset0:136 offset1:153
	v_mul_f32_e32 v2, v28, v185
	v_mul_f32_e32 v3, v28, v186
	v_fma_f32 v2, -v29, v186, v2
	v_fma_f32 v3, v29, v185, v3
	s_nop 0
	v_cvt_pk_f16_f32 v2, v2, v3
	v_mul_f32_e32 v3, v30, v187
	v_mul_f32_e32 v4, v30, v188
	v_fma_f32 v3, -v31, v188, v3
	v_fma_f32 v4, v31, v187, v4
	s_nop 0
	v_cvt_pk_f16_f32 v3, v3, v4
	ds_write2_b32 v1, v2, v3 offset0:204 offset1:221
	v_and_b32_e32 v4, 0xdf, v248
	v_mul_f32_e32 v1, v32, v189
	v_mul_f32_e32 v2, v32, v190
	v_fma_f32 v1, -v33, v190, v1
	v_fma_f32 v2, v33, v189, v2
	v_mad_i32_i24 v248, v249, s87, 0
	v_cvt_pk_f16_f32 v1, v1, v2
	v_mul_f32_e32 v2, v34, v191
	v_mul_f32_e32 v3, v34, v192
	v_fma_f32 v2, -v35, v192, v2
	v_fma_f32 v3, v35, v191, v3
	v_mad_u32_u24 v5, v247, s84, v248
	v_cvt_pk_f16_f32 v2, v2, v3
	ds_write2_b32 v0, v1, v2 offset1:17
	v_mul_f32_e32 v1, v36, v193
	v_mul_f32_e32 v2, v36, v194
	v_fma_f32 v1, -v37, v194, v1
	v_fma_f32 v2, v37, v193, v2
	s_nop 0
	v_cvt_pk_f16_f32 v1, v1, v2
	v_mul_f32_e32 v2, v38, v195
	v_mul_f32_e32 v3, v38, v196
	v_fma_f32 v2, -v39, v196, v2
	v_fma_f32 v3, v39, v195, v3
	s_nop 0
	v_cvt_pk_f16_f32 v2, v2, v3
	ds_write2_b32 v0, v1, v2 offset0:68 offset1:85
	v_mul_f32_e32 v1, v40, v197
	v_mul_f32_e32 v2, v40, v198
	v_fma_f32 v1, -v41, v198, v1
	v_fma_f32 v2, v41, v197, v2
	s_nop 0
	v_cvt_pk_f16_f32 v1, v1, v2
	v_mul_f32_e32 v2, v42, v199
	v_mul_f32_e32 v3, v42, v200
	v_fma_f32 v2, -v43, v200, v2
	v_fma_f32 v3, v43, v199, v3
	s_nop 0
	v_cvt_pk_f16_f32 v2, v2, v3
	ds_write2_b32 v0, v1, v2 offset0:136 offset1:153
	v_mul_f32_e32 v1, v44, v201
	v_mul_f32_e32 v2, v44, v202
	v_fma_f32 v1, -v45, v202, v1
	v_fma_f32 v2, v45, v201, v2
	s_nop 0
	v_cvt_pk_f16_f32 v1, v1, v2
	v_mul_f32_e32 v2, v46, v203
	v_mul_f32_e32 v3, v46, v204
	v_fma_f32 v2, -v47, v204, v2
	v_fma_f32 v3, v47, v203, v3
	s_nop 0
	v_cvt_pk_f16_f32 v2, v2, v3
	ds_write2_b32 v0, v1, v2 offset0:204 offset1:221
	v_lshrrev_b32_e32 v0, 4, v4
	v_add_lshl_u32 v250, v0, v4, 2
	v_add_u32_e32 v6, v5, v250
	v_or_b32_e32 v4, 32, v4
	s_waitcnt lgkmcnt(0)
	s_barrier
	ds_read_b32 v0, v6
	ds_read_b32 v16, v6 offset:17408
	ds_read_b32 v1, v6 offset:2176
	ds_read_b32 v17, v6 offset:19584
	ds_read_b32 v2, v6 offset:4352
	ds_read_b32 v18, v6 offset:21760
	ds_read_b32 v3, v6 offset:6528
	ds_read_b32 v19, v6 offset:23936
	v_lshrrev_b32_e32 v6, 4, v4
	v_add_lshl_u32 v251, v6, v4, 2
	v_add_u32_e32 v4, v5, v251
	ds_read_b32 v20, v4
	ds_read_b32 v36, v4 offset:17408
	ds_read_b32 v21, v4 offset:2176
	ds_read_b32 v37, v4 offset:19584
	ds_read_b32 v22, v4 offset:4352
	ds_read_b32 v38, v4 offset:21760
	ds_read_b32 v23, v4 offset:6528
	ds_read_b32 v39, v4 offset:23936
	v_add_u32_e32 v4, 0x11000, v5
	v_add_u32_e32 v5, v4, v250
	v_add_u32_e32 v4, v4, v251
	ds_read_b32 v32, v5
	ds_read_b32 v52, v5 offset:17408
	ds_read_b32 v33, v5 offset:2176
	ds_read_b32 v53, v5 offset:19584
	ds_read_b32 v34, v5 offset:4352
	ds_read_b32 v54, v5 offset:21760
	ds_read_b32 v35, v5 offset:6528
	ds_read_b32 v55, v5 offset:23936
	ds_read_b32 v48, v4
	ds_read_b32 v128, v4 offset:17408
	ds_read_b32 v49, v4 offset:2176
	ds_read_b32 v129, v4 offset:19584
	ds_read_b32 v50, v4 offset:4352
	ds_read_b32 v130, v4 offset:21760
	ds_read_b32 v51, v4 offset:6528
	ds_read_b32 v131, v4 offset:23936
	s_waitcnt lgkmcnt(14)
	v_mfma_f32_32x32x16_f16 v[0:15], v[76:79], v[0:3], 0
	v_mfma_f32_32x32x16_f16 v[0:15], v[92:95], v[16:19], v[0:15]
	v_mfma_f32_32x32x16_f16 v[16:31], v[76:79], v[20:23], 0
	s_nop 10
	v_cvt_pk_f16_f32 v0, v0, v1
	v_mfma_f32_32x32x16_f16 v[16:31], v[92:95], v[36:39], v[16:31]
	s_waitcnt lgkmcnt(9)
	v_mfma_f32_32x32x16_f16 v[32:47], v[76:79], v[32:35], 0
	s_nop 9
	v_cvt_pk_f16_f32 v1, v16, v17
	s_waitcnt lgkmcnt(8)
	v_mfma_f32_32x32x16_f16 v[32:47], v[92:95], v[52:55], v[32:47]
	s_waitcnt lgkmcnt(1)
	v_mfma_f32_32x32x16_f16 v[48:63], v[76:79], v[48:51], 0
	s_waitcnt lgkmcnt(0)
	v_mfma_f32_32x32x16_f16 v[48:63], v[92:95], v[128:131], v[48:63]
	v_mul_i32_i24_e32 v128, 0x3fc0, v249
	v_mul_u32_u24_e32 v129, 0x880, v247
	v_add3_u32 v128, v248, v128, v129
	v_add_u32_e32 v129, v128, v250
	ds_write_b32 v129, v0 offset:34816
	v_cvt_pk_f16_f32 v0, v2, v3
	ds_write_b32 v129, v0 offset:35904
	v_cvt_pk_f16_f32 v0, v4, v5
	ds_write_b32 v129, v0 offset:39168
	v_cvt_pk_f16_f32 v0, v6, v7
	ds_write_b32 v129, v0 offset:40256
	v_cvt_pk_f16_f32 v0, v8, v9
	ds_write_b32 v129, v0 offset:43520
	v_cvt_pk_f16_f32 v0, v10, v11
	ds_write_b32 v129, v0 offset:44608
	v_cvt_pk_f16_f32 v0, v12, v13
	ds_write_b32 v129, v0 offset:47872
	v_cvt_pk_f16_f32 v0, v14, v15
	ds_write_b32 v129, v0 offset:48960
	v_add_u32_e32 v0, v128, v251
	ds_write_b32 v0, v1 offset:34816
	v_cvt_pk_f16_f32 v1, v18, v19
	ds_write_b32 v0, v1 offset:35904
	v_cvt_pk_f16_f32 v1, v20, v21
	ds_write_b32 v0, v1 offset:39168
	v_cvt_pk_f16_f32 v1, v22, v23
	ds_write_b32 v0, v1 offset:40256
	v_cvt_pk_f16_f32 v1, v24, v25
	ds_write_b32 v0, v1 offset:43520
	v_cvt_pk_f16_f32 v1, v26, v27
	ds_write_b32 v0, v1 offset:44608
	v_cvt_pk_f16_f32 v1, v28, v29
	ds_write_b32 v0, v1 offset:47872
	v_cvt_pk_f16_f32 v1, v30, v31
	ds_write_b32 v0, v1 offset:48960
	v_add_u32_e32 v0, 0x19800, v128
	v_add_u32_e32 v1, v0, v250
	v_cvt_pk_f16_f32 v2, v32, v33
	ds_write_b32 v1, v2
	v_cvt_pk_f16_f32 v2, v34, v35
	ds_write_b32 v1, v2 offset:1088
	v_cvt_pk_f16_f32 v2, v36, v37
	ds_write_b32 v1, v2 offset:4352
	v_cvt_pk_f16_f32 v2, v38, v39
	ds_write_b32 v1, v2 offset:5440
	v_cvt_pk_f16_f32 v2, v40, v41
	ds_write_b32 v1, v2 offset:8704
	v_cvt_pk_f16_f32 v2, v42, v43
	ds_write_b32 v1, v2 offset:9792
	v_cvt_pk_f16_f32 v2, v44, v45
	ds_write_b32 v1, v2 offset:13056
	v_cvt_pk_f16_f32 v2, v46, v47
	ds_write_b32 v1, v2 offset:14144
	v_add_u32_e32 v0, v0, v251
	v_cvt_pk_f16_f32 v1, v48, v49
	ds_write_b32 v0, v1
	v_cvt_pk_f16_f32 v1, v50, v51
	ds_write_b32 v0, v1 offset:1088
	v_cvt_pk_f16_f32 v1, v52, v53
	ds_write_b32 v0, v1 offset:4352
	v_cvt_pk_f16_f32 v1, v54, v55
	ds_write_b32 v0, v1 offset:5440
	v_cvt_pk_f16_f32 v1, v56, v57
	ds_write_b32 v0, v1 offset:8704
	v_cvt_pk_f16_f32 v1, v58, v59
	ds_write_b32 v0, v1 offset:9792
	v_cvt_pk_f16_f32 v1, v60, v61
	ds_write_b32 v0, v1 offset:13056
	v_cvt_pk_f16_f32 v1, v62, v63
	ds_write_b32 v0, v1 offset:14144
	v_lshl_add_u64 v[0:1], v[160:161], 0, s[92:93]
	s_waitcnt lgkmcnt(0)
	s_barrier
	global_load_dwordx4 v[12:15], v[0:1], off
	global_load_ushort v24, v[0:1], off offset:-2
	global_load_ushort v25, v[0:1], off offset:16
	v_mov_b32_e32 v0, 0
	v_mov_b32_e32 v8, 0
	v_mov_b32_e32 v9, 0
	v_mov_b32_e32 v10, 0
	v_mov_b32_e32 v11, 0
	s_cbranch_vccnz .LBB0_1802
	s_add_i32 s92, s8, s51
	s_ashr_i32 s93, s92, 31
	s_lshl_b64 s[92:93], s[92:93], 13
	v_lshl_add_u64 v[2:3], v[160:161], 0, s[92:93]
	global_load_dwordx4 v[8:11], v[2:3], off
